# LRU t4 loops software-pipelined (next 4-row batch prefetched into spare VGPRs)
# speedup vs baseline: 1.0784x; 1.0019x over previous
; __device__ __forceinline__ float softplusf_(float x) { return fmaxf(x, 0.f) + __logf(1.0f + __expf(-fabsf(x))); }
; __device__ __forceinline__ Seq seq_of(int p, int q) { Seq s; if (q < 2) { s.row0 = q * SEQ; s.T = SEQ; s.sample = 0; s.b = 2 * p + q; } else { s.row0 = 16384 + (q - 2) * DSEQ; s.T = DSEQ; s.sample = 1; s.b = q - 2; } return s; }
; __device__ __forceinline__ Seg seg_of(int s) { Seg g; if (s < 256) { g.q = s >> 7; g.c = s & 127; g.row0 = g.q * SEQ + g.c * 64; g.n = 64; g.nch = 128; } else { g.q = 2 + (s - 256); g.c = 0; g.row0 = 16384 + (s - 256) * DSEQ; g.n = DSEQ; g.nch = 1; } return g; }
; template <int FINAL>
; __device__ __forceinline__ void phase_lru(const Ctx& c, int p, int l) {
;     ...
;         const int s = i >> 7, ch = 8 * (i & 127); const Seg g = seg_of(s); const Seq sq = seq_of(p, g.q);
;         float ba[8], bx[8], c1[8], A[8], B[8];
; #pragma unroll
;         for (int j = 0; j < 8; ++j) { ba[j] = inp(c, I_LBA)[(size_t)l * D + ch + j]; bx[j] = inp(c, I_LBX)[(size_t)l * D + ch + j]; c1[j] = -8.0f * softplusf_(-inp(c, I_LLAM)[(size_t)l * D + ch + j]); A[j] = 1.f; B[j] = 0.f; }
.LBB0_1076:
	s_or_b64 exec, exec, s[2:3]
	v_lshlrev_b32_e32 v0, 1, v127
	v_and_b32_e32 v30, 0x7f0, v0
	v_lshlrev_b32_e32 v0, 3, v126
	v_and_b32_e32 v128, 0x3f8, v0
	v_readlane_b32 s2, v254, 23
	v_readlane_b32 s3, v254, 24
	v_mov_b32_e32 v1, v31
	v_or_b32_e32 v0, s2, v128
	s_waitcnt lgkmcnt(2)
	v_readfirstlane_b32 s2, v28
	v_readfirstlane_b32 s3, v29
	s_waitcnt vmcnt(5)
	v_lshlrev_b64 v[18:19], 2, v[0:1]
	s_mov_b32 s0, 0xbfb8aa3b
	v_lshl_add_u64 v[4:5], s[2:3], 0, v[18:19]
	s_waitcnt lgkmcnt(1)
	v_readfirstlane_b32 s2, v68
	v_readfirstlane_b32 s3, v69
	global_load_dwordx4 v[0:3], v[4:5], off
	s_nop 0
	global_load_dwordx4 v[4:7], v[4:5], off offset:16
	v_lshl_add_u64 v[12:13], s[2:3], 0, v[18:19]
	s_waitcnt lgkmcnt(0)
	v_readfirstlane_b32 s2, v70
	v_readfirstlane_b32 s3, v71
	global_load_dwordx4 v[8:11], v[12:13], off
	s_nop 0
	global_load_dwordx4 v[12:15], v[12:13], off offset:16
	v_lshl_add_u64 v[18:19], s[2:3], 0, v[18:19]
	global_load_dwordx4 v[20:23], v[18:19], off offset:16
	global_load_dwordx4 v[24:27], v[18:19], off
	s_mov_b32 s16, 0x800000
	s_mov_b32 s17, 0x3f317217
	s_mov_b32 s18, 0x7f800000
	s_mov_b32 s15, 0
	s_waitcnt vmcnt(0)
	v_mul_f32_e64 v18, |v24|, s0
	v_exp_f32_e32 v19, v18
	v_max_f32_e64 v17, -v24, -v24
	v_max_f32_e32 v17, 0, v17
	v_mov_b32_e32 v18, 1.0
	v_add_f32_e32 v19, 1.0, v19
	v_cmp_gt_f32_e32 vcc, s16, v19
	v_mov_b32_e32 v32, v18
	v_mov_b32_e32 v33, v18
	v_cndmask_b32_e64 v24, 0, 32, vcc
	v_ldexp_f32 v19, v19, v24
	v_log_f32_e32 v19, v19
	v_mov_b32_e32 v34, v18
	v_mov_b32_e32 v35, v18
	v_mul_f32_e32 v24, 0x3f317217, v19
	v_fma_f32 v24, v19, s17, -v24
	v_fmac_f32_e32 v24, 0x3377d1cf, v19
	v_fmac_f32_e32 v24, 0x3f317217, v19
	v_cmp_lt_f32_e64 s[2:3], |v19|, s18
	s_nop 1
	v_cndmask_b32_e64 v19, v19, v24, s[2:3]
	v_cndmask_b32_e32 v24, 0, v178, vcc
	v_sub_f32_e32 v19, v19, v24
	v_add_f32_e32 v17, v17, v19
	v_mul_f32_e64 v19, |v25|, s0
	v_exp_f32_e32 v19, v19
	v_mul_f32_e32 v129, 0xc1000000, v17
	v_max_f32_e64 v17, -v25, -v25
	v_max_f32_e32 v17, 0, v17
	v_add_f32_e32 v19, 1.0, v19
	v_cmp_gt_f32_e32 vcc, s16, v19
	s_nop 1
	v_cndmask_b32_e64 v24, 0, 32, vcc
	v_ldexp_f32 v19, v19, v24
	v_log_f32_e32 v19, v19
	s_nop 0
	v_mul_f32_e32 v24, 0x3f317217, v19
	v_fma_f32 v24, v19, s17, -v24
	v_fmac_f32_e32 v24, 0x3377d1cf, v19
	v_fmac_f32_e32 v24, 0x3f317217, v19
	v_cmp_lt_f32_e64 s[2:3], |v19|, s18
	s_nop 1
	v_cndmask_b32_e64 v19, v19, v24, s[2:3]
	v_cndmask_b32_e32 v24, 0, v178, vcc
	v_sub_f32_e32 v19, v19, v24
	v_add_f32_e32 v17, v17, v19
	v_mul_f32_e64 v19, |v26|, s0
	v_exp_f32_e32 v19, v19
	v_mul_f32_e32 v130, 0xc1000000, v17
	v_max_f32_e64 v17, -v26, -v26
	v_max_f32_e32 v17, 0, v17
	v_add_f32_e32 v19, 1.0, v19
	v_cmp_gt_f32_e32 vcc, s16, v19
	s_nop 1
	v_cndmask_b32_e64 v24, 0, 32, vcc
	v_ldexp_f32 v19, v19, v24
	v_log_f32_e32 v19, v19
	s_nop 0
	v_mul_f32_e32 v24, 0x3f317217, v19
	v_fma_f32 v24, v19, s17, -v24
	v_fmac_f32_e32 v24, 0x3377d1cf, v19
	v_fmac_f32_e32 v24, 0x3f317217, v19
	v_cmp_lt_f32_e64 s[2:3], |v19|, s18
	s_nop 1
	v_cndmask_b32_e64 v19, v19, v24, s[2:3]
	v_cndmask_b32_e32 v24, 0, v178, vcc
	v_sub_f32_e32 v19, v19, v24
	v_add_f32_e32 v17, v17, v19
	v_mul_f32_e64 v19, |v27|, s0
	v_exp_f32_e32 v19, v19
	v_mul_f32_e32 v131, 0xc1000000, v17
	v_max_f32_e64 v17, -v27, -v27
	v_max_f32_e32 v17, 0, v17
	v_add_f32_e32 v19, 1.0, v19
	v_cmp_gt_f32_e32 vcc, s16, v19
	s_nop 1
	v_cndmask_b32_e64 v24, 0, 32, vcc
	v_ldexp_f32 v19, v19, v24
	v_log_f32_e32 v19, v19
	s_nop 0
	v_mul_f32_e32 v24, 0x3f317217, v19
	v_fma_f32 v24, v19, s17, -v24
	v_fmac_f32_e32 v24, 0x3377d1cf, v19
	v_fmac_f32_e32 v24, 0x3f317217, v19
	v_cmp_lt_f32_e64 s[2:3], |v19|, s18
	s_nop 1
	v_cndmask_b32_e64 v19, v19, v24, s[2:3]
	v_cndmask_b32_e32 v24, 0, v178, vcc
	v_sub_f32_e32 v19, v19, v24
	v_add_f32_e32 v17, v17, v19
	v_mul_f32_e64 v19, |v20|, s0
	v_exp_f32_e32 v19, v19
	v_mul_f32_e32 v132, 0xc1000000, v17
	v_max_f32_e64 v17, -v20, -v20
	v_max_f32_e32 v17, 0, v17
	v_add_f32_e32 v19, 1.0, v19
	v_cmp_gt_f32_e32 vcc, s16, v19
	s_nop 1
	v_cndmask_b32_e64 v20, 0, 32, vcc
	v_ldexp_f32 v19, v19, v20
	v_log_f32_e32 v19, v19
	s_nop 0
	v_mul_f32_e32 v20, 0x3f317217, v19
	v_fma_f32 v20, v19, s17, -v20
	v_fmac_f32_e32 v20, 0x3377d1cf, v19
	v_fmac_f32_e32 v20, 0x3f317217, v19
	v_cmp_lt_f32_e64 s[2:3], |v19|, s18
	s_nop 1
	v_cndmask_b32_e64 v19, v19, v20, s[2:3]
	v_cndmask_b32_e32 v20, 0, v178, vcc
	v_sub_f32_e32 v19, v19, v20
	v_add_f32_e32 v17, v17, v19
	v_mul_f32_e64 v19, |v21|, s0
	v_exp_f32_e32 v19, v19
	v_mul_f32_e32 v133, 0xc1000000, v17
	v_max_f32_e64 v17, -v21, -v21
	v_max_f32_e32 v17, 0, v17
	v_add_f32_e32 v19, 1.0, v19
	v_cmp_gt_f32_e32 vcc, s16, v19
	s_nop 1
	v_cndmask_b32_e64 v20, 0, 32, vcc
	v_ldexp_f32 v19, v19, v20
	v_log_f32_e32 v19, v19
	s_nop 0
	v_mul_f32_e32 v20, 0x3f317217, v19
	v_fma_f32 v20, v19, s17, -v20
	v_fmac_f32_e32 v20, 0x3377d1cf, v19
	v_fmac_f32_e32 v20, 0x3f317217, v19
	v_cmp_lt_f32_e64 s[2:3], |v19|, s18
	s_nop 1
	v_cndmask_b32_e64 v19, v19, v20, s[2:3]
	v_cndmask_b32_e32 v20, 0, v178, vcc
	v_sub_f32_e32 v19, v19, v20
	v_add_f32_e32 v17, v17, v19
	v_mul_f32_e64 v19, |v22|, s0
	v_exp_f32_e32 v19, v19
	v_mul_f32_e32 v134, 0xc1000000, v17
	v_max_f32_e64 v17, -v22, -v22
	v_max_f32_e32 v17, 0, v17
	v_add_f32_e32 v19, 1.0, v19
	v_cmp_gt_f32_e32 vcc, s16, v19
	s_nop 1
	v_cndmask_b32_e64 v20, 0, 32, vcc
	v_ldexp_f32 v19, v19, v20
	v_log_f32_e32 v19, v19
	s_nop 0
	v_mul_f32_e32 v20, 0x3f317217, v19
	v_fma_f32 v20, v19, s17, -v20
	v_fmac_f32_e32 v20, 0x3377d1cf, v19
	v_fmac_f32_e32 v20, 0x3f317217, v19
	v_cmp_lt_f32_e64 s[2:3], |v19|, s18
	s_nop 1
	v_cndmask_b32_e64 v19, v19, v20, s[2:3]
	v_cndmask_b32_e32 v20, 0, v178, vcc
	v_sub_f32_e32 v19, v19, v20
; __device__ __forceinline__ void unpack8(const u32x4 w, float (&f)[8]) { f[0] = bflo(w.x); f[1] = bfhi(w.x); f[2] = bflo(w.y); f[3] = bfhi(w.y); f[4] = bflo(w.z); f[5] = bfhi(w.z); f[6] = bflo(w.w); f[7] = bfhi(w.w); }
; __device__ __forceinline__ float sigmoidf_(float x) { return __builtin_amdgcn_rcpf(1.0f + __expf(-x)); }
; __device__ __forceinline__ float softplusf_(float x) { return fmaxf(x, 0.f) + __logf(1.0f + __expf(-fabsf(x))); }
; template <int FINAL>
; __device__ __forceinline__ void phase_lru(const Ctx& c, int p, int l) {
;     ...
;         for (int j = 0; j < 8; ++j) { ba[j] = inp(c, I_LBA)[(size_t)l * D + ch + j]; bx[j] = inp(c, I_LBX)[(size_t)l * D + ch + j]; c1[j] = -8.0f * softplusf_(-inp(c, I_LLAM)[(size_t)l * D + ch + j]); A[j] = 1.f; B[j] = 0.f; }
;         if (FINAL) {
;             if (sq.sample) {
; #pragma unroll
;                 for (int j = 0; j < 8; ++j) B[j] = inp(c, I_SLRU)[((size_t)l * DB + sq.b) * D + ch + j]; }
;             for (int cp = 0; cp < g.c; ++cp) { const float* ca = car + (size_t)(s - g.c + cp) * 2048 + ch;
; #pragma unroll
;                 for (int j = 0; j < 8; ++j) B[j] = ca[j] * B[j] + ca[1024 + j]; }
;         }
;         for (int t4 = 0; t4 < g.n; t4 += 4) {
;           u32x4 rx[4], rr[4], ri[4];
; #pragma unroll
;           for (int u = 0; u < 4; ++u) { const size_t row = (size_t)(g.row0 + t4 + u); rx[u] = *(const u32x4*)(Z + row * ZW + C_LRU + ch); rr[u] = *(const u32x4*)(T + row * 2048 + ch); ri[u] = *(const u32x4*)(T + row * 2048 + 1024 + ch); }
; #pragma unroll
;           for (int u = 0; u < 4; ++u) {
;             const size_t row = (size_t)(g.row0 + t4 + u); float x[8], rp[8], ip[8];
;             unpack8(rx[u], x); unpack8(rr[u], rp); unpack8(ri[u], ip);
; #pragma unroll
;             for (int j = 0; j < 8; ++j) { const float la = c1[j] * sigmoidf_(rp[j] + ba[j]), a = __expf(la), bt = __builtin_amdgcn_sqrtf(fmaxf(1.0f - __expf(2.0f * la), 0.f)) * sigmoidf_(ip[j] + bx[j]) * x[j];
;                 B[j] = a * B[j] + bt; A[j] *= a; x[j] = B[j]; }
	v_add_f32_e32 v17, v17, v19
	v_mul_f32_e64 v19, |v23|, s0
	v_exp_f32_e32 v19, v19
	v_mul_f32_e32 v135, 0xc1000000, v17
	v_max_f32_e64 v17, -v23, -v23
	v_max_f32_e32 v17, 0, v17
	v_add_f32_e32 v19, 1.0, v19
	v_cmp_gt_f32_e32 vcc, s16, v19
	s_nop 1
	v_cndmask_b32_e64 v20, 0, 32, vcc
	v_ldexp_f32 v19, v19, v20
	v_log_f32_e32 v19, v19
	s_nop 0
	v_mul_f32_e32 v20, 0x3f317217, v19
	v_fma_f32 v20, v19, s17, -v20
	v_fmac_f32_e32 v20, 0x3377d1cf, v19
	v_fmac_f32_e32 v20, 0x3f317217, v19
	v_cmp_lt_f32_e64 s[2:3], |v19|, s18
	s_mov_b64 s[16:17], 0x4000
	s_mov_b64 s[18:19], 0x10800
	v_cndmask_b32_e64 v19, v19, v20, s[2:3]
	v_cndmask_b32_e32 v20, 0, v178, vcc
	v_sub_f32_e32 v19, v19, v20
	v_add_f32_e32 v17, v17, v19
	v_mul_f32_e32 v144, 0xc1000000, v17
	v_ashrrev_i32_e32 v17, 31, v16
	v_lshlrev_b64 v[20:21], 12, v[16:17]
	v_lshl_add_u64 v[74:75], s[82:83], 0, v[20:21]
	v_mov_b64_e32 v[20:21], s[82:83]
	v_mad_i64_i32 v[76:77], s[2:3], v16, s33, v[20:21]
	v_mov_b32_e32 v20, 0
	s_mov_b64 s[2:3], 0
	v_mov_b32_e32 v19, v18
	v_mov_b32_e32 v16, v18
	v_mov_b32_e32 v17, v18
	v_mov_b32_e32 v21, v20
	v_mov_b32_e32 v22, v20
	v_mov_b32_e32 v23, v20
	v_mov_b32_e32 v24, v20
	v_mov_b32_e32 v25, v20
	v_mov_b32_e32 v26, v20
	v_mov_b32_e32 v27, v20
	v_lshl_add_u64 v[244:245], v[76:77], 0, v[30:31]
	v_lshl_add_u64 v[246:247], v[74:75], 0, v[30:31]
	v_add_co_u32_e32 v248, vcc, 0x6288000, v244
	s_nop 1
	v_addc_co_u32_e32 v249, vcc, 0, v245, vcc
	v_add_co_u32_e32 v250, vcc, 0x628c000, v244
	s_nop 1
	v_addc_co_u32_e32 v251, vcc, 0, v245, vcc
	v_add_co_u32_e32 v252, vcc, 0x6290000, v244
	s_nop 1
	v_addc_co_u32_e32 v253, vcc, 0, v245, vcc
	v_add_co_u32_e32 v194, vcc, 0x6294000, v244
	s_nop 1
	v_addc_co_u32_e32 v195, vcc, 0, v245, vcc
	v_add_co_u32_e32 v244, vcc, 0x16ea9000, v246
	s_nop 1
	v_addc_co_u32_e32 v245, vcc, 0, v247, vcc
	v_add_co_u32_e32 v246, vcc, 0x16eab000, v246
	s_nop 1
	v_addc_co_u32_e32 v247, vcc, 0, v247, vcc
	global_load_dwordx4 v[196:199], v[248:249], off
	global_load_dwordx4 v[200:203], v[244:245], off offset:-4096
	global_load_dwordx4 v[204:207], v[244:245], off offset:-2048
	global_load_dwordx4 v[208:211], v[250:251], off offset:512
	global_load_dwordx4 v[212:215], v[244:245], off
	global_load_dwordx4 v[216:219], v[244:245], off offset:2048
	global_load_dwordx4 v[220:223], v[252:253], off offset:1024
	global_load_dwordx4 v[224:227], v[246:247], off offset:-4096
	global_load_dwordx4 v[228:231], v[246:247], off offset:-2048
	global_load_dwordx4 v[232:235], v[194:195], off offset:1536
	global_load_dwordx4 v[236:239], v[246:247], off
	global_load_dwordx4 v[240:243], v[246:247], off offset:2048
.LBB0_1077:
	s_add_i32 s15, s15, 4
	v_lshl_add_u64 v[74:75], v[74:75], 0, s[16:17]
	v_lshl_add_u64 v[76:77], v[76:77], 0, s[18:19]
	s_waitcnt vmcnt(0)
	v_mov_b64_e32 v[36:37], v[196:197]
	v_mov_b64_e32 v[38:39], v[198:199]
	v_mov_b64_e32 v[78:79], v[200:201]
	v_mov_b64_e32 v[80:81], v[202:203]
	v_mov_b64_e32 v[82:83], v[204:205]
	v_mov_b64_e32 v[84:85], v[206:207]
	v_mov_b64_e32 v[40:41], v[208:209]
	v_mov_b64_e32 v[42:43], v[210:211]
	v_mov_b64_e32 v[102:103], v[212:213]
	v_mov_b64_e32 v[104:105], v[214:215]
	v_mov_b64_e32 v[106:107], v[216:217]
	v_mov_b64_e32 v[108:109], v[218:219]
	v_mov_b64_e32 v[44:45], v[220:221]
	v_mov_b64_e32 v[46:47], v[222:223]
	v_mov_b64_e32 v[64:65], v[224:225]
	v_mov_b64_e32 v[66:67], v[226:227]
	v_mov_b64_e32 v[60:61], v[228:229]
	v_mov_b64_e32 v[62:63], v[230:231]
	v_mov_b64_e32 v[48:49], v[232:233]
	v_mov_b64_e32 v[50:51], v[234:235]
	v_mov_b64_e32 v[56:57], v[236:237]
	v_mov_b64_e32 v[58:59], v[238:239]
	v_mov_b64_e32 v[52:53], v[240:241]
	v_mov_b64_e32 v[54:55], v[242:243]
	v_lshl_add_u64 v[244:245], v[76:77], 0, v[30:31]
	v_lshl_add_u64 v[246:247], v[74:75], 0, v[30:31]
	v_add_co_u32_e32 v248, vcc, 0x6288000, v244
	s_nop 1
	v_addc_co_u32_e32 v249, vcc, 0, v245, vcc
	v_add_co_u32_e32 v250, vcc, 0x628c000, v244
	s_nop 1
	v_addc_co_u32_e32 v251, vcc, 0, v245, vcc
	v_add_co_u32_e32 v252, vcc, 0x6290000, v244
	s_nop 1
	v_addc_co_u32_e32 v253, vcc, 0, v245, vcc
	v_add_co_u32_e32 v194, vcc, 0x6294000, v244
	s_nop 1
	v_addc_co_u32_e32 v195, vcc, 0, v245, vcc
	v_add_co_u32_e32 v244, vcc, 0x16ea9000, v246
	s_nop 1
	v_addc_co_u32_e32 v245, vcc, 0, v247, vcc
	v_add_co_u32_e32 v246, vcc, 0x16eab000, v246
	s_nop 1
	v_addc_co_u32_e32 v247, vcc, 0, v247, vcc
	global_load_dwordx4 v[196:199], v[248:249], off
	global_load_dwordx4 v[200:203], v[244:245], off offset:-4096
	global_load_dwordx4 v[204:207], v[244:245], off offset:-2048
	global_load_dwordx4 v[208:211], v[250:251], off offset:512
	global_load_dwordx4 v[212:215], v[244:245], off
	global_load_dwordx4 v[216:219], v[244:245], off offset:2048
	global_load_dwordx4 v[220:223], v[252:253], off offset:1024
	global_load_dwordx4 v[224:227], v[246:247], off offset:-4096
	global_load_dwordx4 v[228:231], v[246:247], off offset:-2048
	global_load_dwordx4 v[232:235], v[194:195], off offset:1536
	global_load_dwordx4 v[236:239], v[246:247], off
	global_load_dwordx4 v[240:243], v[246:247], off offset:2048
	v_cmp_ge_u32_e32 vcc, s15, v73
	s_or_b64 s[2:3], vcc, s[2:3]
	v_lshlrev_b32_e32 v86, 16, v78
	v_add_f32_e32 v86, v0, v86
	v_mul_f32_e32 v86, 0xbfb8aa3b, v86
	v_exp_f32_e32 v86, v86
	v_and_b32_e32 v78, 0xffff0000, v78
	v_add_f32_e32 v78, v1, v78
	v_mul_f32_e32 v78, 0xbfb8aa3b, v78
	v_add_f32_e32 v86, 1.0, v86
	v_rcp_f32_e32 v86, v86
	v_exp_f32_e32 v78, v78
	v_lshlrev_b32_e32 v88, 16, v82
	v_and_b32_e32 v82, 0xffff0000, v82
	v_mul_f32_e32 v86, v129, v86
	v_mul_f32_e32 v92, 0x3fb8aa3b, v86
	v_add_f32_e32 v86, v86, v86
	v_mul_f32_e32 v86, 0x3fb8aa3b, v86
	v_exp_f32_e32 v86, v86
	v_add_f32_e32 v78, 1.0, v78
; __device__ __forceinline__ void unpack8(const u32x4 w, float (&f)[8]) { f[0] = bflo(w.x); f[1] = bfhi(w.x); f[2] = bflo(w.y); f[3] = bfhi(w.y); f[4] = bflo(w.z); f[5] = bfhi(w.z); f[6] = bflo(w.w); f[7] = bfhi(w.w); }
; __device__ __forceinline__ float sigmoidf_(float x) { return __builtin_amdgcn_rcpf(1.0f + __expf(-x)); }
; template <int FINAL>
; __device__ __forceinline__ void phase_lru(const Ctx& c, int p, int l) {
;     ...
;           for (int u = 0; u < 4; ++u) {
;             const size_t row = (size_t)(g.row0 + t4 + u); float x[8], rp[8], ip[8];
;             unpack8(rx[u], x); unpack8(rr[u], rp); unpack8(ri[u], ip);
; #pragma unroll
;             for (int j = 0; j < 8; ++j) { const float la = c1[j] * sigmoidf_(rp[j] + ba[j]), a = __expf(la), bt = __builtin_amdgcn_sqrtf(fmaxf(1.0f - __expf(2.0f * la), 0.f)) * sigmoidf_(ip[j] + bx[j]) * x[j];
;                 B[j] = a * B[j] + bt; A[j] *= a; x[j] = B[j]; }
	v_rcp_f32_e32 v78, v78
	v_lshlrev_b32_e32 v87, 16, v79
	v_sub_f32_e32 v86, 1.0, v86
	v_max_f32_e32 v86, 0, v86
	v_sqrt_f32_e32 v98, v86
	v_add_f32_e32 v86, v8, v88
	v_mul_f32_e32 v86, 0xbfb8aa3b, v86
	v_exp_f32_e32 v86, v86
	v_mul_f32_e32 v78, v130, v78
	v_lshlrev_b32_e32 v89, 16, v83
	v_exp_f32_e32 v94, v92
	v_add_f32_e32 v86, 1.0, v86
	v_rcp_f32_e32 v100, v86
	v_mul_f32_e32 v86, 0x3fb8aa3b, v78
	v_add_f32_e32 v78, v78, v78
	v_mul_f32_e32 v78, 0x3fb8aa3b, v78
	v_exp_f32_e32 v78, v78
	v_and_b32_e32 v79, 0xffff0000, v79
	v_and_b32_e32 v83, 0xffff0000, v83
	v_lshlrev_b32_e32 v90, 16, v80
	v_sub_f32_e32 v78, 1.0, v78
	v_max_f32_e32 v78, 0, v78
	v_sqrt_f32_e32 v99, v78
	v_add_f32_e32 v78, v9, v82
	v_mul_f32_e32 v78, 0xbfb8aa3b, v78
	v_exp_f32_e32 v78, v78
	v_lshlrev_b32_e32 v91, 16, v84
	v_exp_f32_e32 v95, v86
	v_and_b32_e32 v80, 0xffff0000, v80
	v_add_f32_e32 v78, 1.0, v78
	v_rcp_f32_e32 v101, v78
	v_add_f32_e32 v78, v2, v87
	v_mul_f32_e32 v78, 0xbfb8aa3b, v78
	v_exp_f32_e32 v78, v78
	v_and_b32_e32 v84, 0xffff0000, v84
	v_lshlrev_b32_e32 v110, 16, v81
	v_lshlrev_b32_e32 v112, 16, v106
	v_add_f32_e32 v78, 1.0, v78
	v_rcp_f32_e32 v78, v78
	v_and_b32_e32 v106, 0xffff0000, v106
	v_lshlrev_b32_e32 v111, 16, v85
	v_lshlrev_b32_e32 v113, 16, v107
	v_mul_f32_e32 v78, v131, v78
	v_mul_f32_e32 v82, 0x3fb8aa3b, v78
	v_add_f32_e32 v78, v78, v78
	v_mul_f32_e32 v78, 0x3fb8aa3b, v78
	v_exp_f32_e32 v78, v78
	v_exp_f32_e32 v88, v82
	v_and_b32_e32 v107, 0xffff0000, v107
	v_lshlrev_b32_e32 v114, 16, v104
	v_sub_f32_e32 v78, 1.0, v78
	v_max_f32_e32 v78, 0, v78
	v_sqrt_f32_e32 v92, v78
	v_add_f32_e32 v78, v10, v89
	v_mul_f32_e32 v78, 0xbfb8aa3b, v78
	v_exp_f32_e32 v78, v78
	v_lshlrev_b32_e32 v115, 16, v108
	v_and_b32_e32 v104, 0xffff0000, v104
	v_and_b32_e32 v108, 0xffff0000, v108
	v_add_f32_e32 v78, 1.0, v78
	v_rcp_f32_e32 v96, v78
	v_add_f32_e32 v78, v3, v79
	v_mul_f32_e32 v78, 0xbfb8aa3b, v78
	v_exp_f32_e32 v78, v78
	v_lshlrev_b32_e32 v136, 16, v105
	v_lshlrev_b32_e32 v160, 16, v63
	v_and_b32_e32 v161, 0xffff0000, v63
	v_add_f32_e32 v78, 1.0, v78
	v_rcp_f32_e32 v78, v78
	v_lshlrev_b32_e32 v154, 16, v66
	v_and_b32_e32 v155, 0xffff0000, v66
	v_lshlrev_b32_e32 v66, 16, v60
	v_mul_f32_e32 v78, v132, v78
	v_mul_f32_e32 v79, 0x3fb8aa3b, v78
	v_add_f32_e32 v78, v78, v78
	v_mul_f32_e32 v78, 0x3fb8aa3b, v78
	v_exp_f32_e32 v78, v78
	v_exp_f32_e32 v89, v79
	v_and_b32_e32 v60, 0xffff0000, v60
	v_add_f32_e32 v60, v9, v60
	v_sub_f32_e32 v78, 1.0, v78
	v_max_f32_e32 v78, 0, v78
	v_sqrt_f32_e32 v93, v78
	v_add_f32_e32 v78, v11, v83
	v_mul_f32_e32 v78, 0xbfb8aa3b, v78
	v_exp_f32_e32 v78, v78
	v_mul_f32_e32 v60, 0xbfb8aa3b, v60
	v_exp_f32_e32 v60, v60
	v_lshlrev_b32_e32 v145, 16, v65
	v_add_f32_e32 v78, 1.0, v78
	v_rcp_f32_e32 v97, v78
	v_add_f32_e32 v78, v4, v90
	v_mul_f32_e32 v78, 0xbfb8aa3b, v78
	v_exp_f32_e32 v78, v78
	v_add_f32_e32 v60, 1.0, v60
	v_rcp_f32_e32 v147, v60
	v_add_f32_e32 v60, v2, v145
	v_add_f32_e32 v78, 1.0, v78
	v_rcp_f32_e32 v78, v78
	v_mul_f32_e32 v60, 0xbfb8aa3b, v60
	v_exp_f32_e32 v60, v60
	v_lshlrev_b32_e32 v158, 16, v67
	v_mul_f32_e32 v78, v133, v78
	v_mul_f32_e32 v79, 0x3fb8aa3b, v78
	v_add_f32_e32 v78, v78, v78
	v_mul_f32_e32 v78, 0x3fb8aa3b, v78
	v_exp_f32_e32 v78, v78
	v_exp_f32_e32 v82, v79
	v_add_f32_e32 v60, 1.0, v60
	v_rcp_f32_e32 v60, v60
	v_sub_f32_e32 v78, 1.0, v78
	v_max_f32_e32 v78, 0, v78
	v_sqrt_f32_e32 v86, v78
	v_add_f32_e32 v78, v12, v91
	v_mul_f32_e32 v78, 0xbfb8aa3b, v78
	v_exp_f32_e32 v78, v78
	v_mul_f32_e32 v60, v131, v60
	v_and_b32_e32 v159, 0xffff0000, v67
	v_lshlrev_b32_e32 v67, 16, v61
	v_add_f32_e32 v78, 1.0, v78
	v_rcp_f32_e32 v90, v78
	v_add_f32_e32 v78, v5, v80
	v_mul_f32_e32 v78, 0xbfb8aa3b, v78
	v_exp_f32_e32 v78, v78
	v_and_b32_e32 v65, 0xffff0000, v65
	v_and_b32_e32 v61, 0xffff0000, v61
	v_lshlrev_b32_e32 v156, 16, v62
	v_add_f32_e32 v78, 1.0, v78
	v_rcp_f32_e32 v78, v78
	v_and_b32_e32 v62, 0xffff0000, v62
	v_lshlrev_b32_e32 v137, 16, v109
	v_lshlrev_b32_e32 v145, 16, v56
	v_mul_f32_e32 v78, v134, v78
	v_mul_f32_e32 v79, 0x3fb8aa3b, v78
	v_add_f32_e32 v78, v78, v78
	v_mul_f32_e32 v78, 0x3fb8aa3b, v78
	v_exp_f32_e32 v78, v78
	v_exp_f32_e32 v83, v79
	v_lshlrev_b32_e32 v187, 16, v53
	v_and_b32_e32 v188, 0xffff0000, v53
	v_sub_f32_e32 v78, 1.0, v78
	v_max_f32_e32 v78, 0, v78
	v_sqrt_f32_e32 v87, v78
	v_add_f32_e32 v78, v13, v84
	v_mul_f32_e32 v78, 0xbfb8aa3b, v78
	v_exp_f32_e32 v78, v78
	v_lshlrev_b32_e32 v189, 16, v54
	v_and_b32_e32 v190, 0xffff0000, v54
	v_and_b32_e32 v184, 0xffff0000, v58
	v_add_f32_e32 v78, 1.0, v78
	v_rcp_f32_e32 v91, v78
	v_add_f32_e32 v78, v6, v110
	v_lshlrev_b32_e32 v110, 16, v102
	v_add_f32_e32 v110, v0, v110
	v_mul_f32_e32 v110, 0xbfb8aa3b, v110
	v_exp_f32_e32 v110, v110
	v_and_b32_e32 v102, 0xffff0000, v102
	v_add_f32_e32 v102, v1, v102
	v_mul_f32_e32 v102, 0xbfb8aa3b, v102
	v_add_f32_e32 v110, 1.0, v110
	v_rcp_f32_e32 v110, v110
	v_exp_f32_e32 v102, v102
	v_mul_f32_e32 v78, 0xbfb8aa3b, v78
	v_exp_f32_e32 v78, v78
	v_mul_f32_e32 v110, v129, v110
	v_mul_f32_e32 v116, 0x3fb8aa3b, v110
	v_add_f32_e32 v110, v110, v110
	v_mul_f32_e32 v110, 0x3fb8aa3b, v110
	v_exp_f32_e32 v110, v110
	v_add_f32_e32 v102, 1.0, v102
	v_rcp_f32_e32 v102, v102
	v_add_f32_e32 v78, 1.0, v78
	v_sub_f32_e32 v110, 1.0, v110
	v_max_f32_e32 v110, 0, v110
	v_sqrt_f32_e32 v122, v110
	v_add_f32_e32 v110, v8, v112
	v_mul_f32_e32 v110, 0xbfb8aa3b, v110
	v_exp_f32_e32 v110, v110
	v_mul_f32_e32 v102, v130, v102
	v_rcp_f32_e32 v78, v78
	v_exp_f32_e32 v118, v116
	v_add_f32_e32 v110, 1.0, v110
	v_rcp_f32_e32 v124, v110
	v_mul_f32_e32 v110, 0x3fb8aa3b, v102
	v_add_f32_e32 v102, v102, v102
	v_mul_f32_e32 v102, 0x3fb8aa3b, v102
; __device__ __forceinline__ void unpack8(const u32x4 w, float (&f)[8]) { f[0] = bflo(w.x); f[1] = bfhi(w.x); f[2] = bflo(w.y); f[3] = bfhi(w.y); f[4] = bflo(w.z); f[5] = bfhi(w.z); f[6] = bflo(w.w); f[7] = bfhi(w.w); }
; __device__ __forceinline__ float sigmoidf_(float x) { return __builtin_amdgcn_rcpf(1.0f + __expf(-x)); }
; template <int FINAL>
; __device__ __forceinline__ void phase_lru(const Ctx& c, int p, int l) {
;     ...
;           for (int u = 0; u < 4; ++u) {
;             const size_t row = (size_t)(g.row0 + t4 + u); float x[8], rp[8], ip[8];
;             unpack8(rx[u], x); unpack8(rr[u], rp); unpack8(ri[u], ip);
; #pragma unroll
;             for (int j = 0; j < 8; ++j) { const float la = c1[j] * sigmoidf_(rp[j] + ba[j]), a = __expf(la), bt = __builtin_amdgcn_sqrtf(fmaxf(1.0f - __expf(2.0f * la), 0.f)) * sigmoidf_(ip[j] + bx[j]) * x[j];
;                 B[j] = a * B[j] + bt; A[j] *= a; x[j] = B[j]; }
	v_exp_f32_e32 v102, v102
	v_mul_f32_e32 v79, v135, v78
	v_mul_f32_e32 v78, 0x3fb8aa3b, v79
	v_add_f32_e32 v79, v79, v79
	v_sub_f32_e32 v102, 1.0, v102
	v_mul_f32_e32 v79, 0x3fb8aa3b, v79
	v_max_f32_e32 v102, 0, v102
	v_exp_f32_e32 v79, v79
	v_sqrt_f32_e32 v123, v102
	v_add_f32_e32 v102, v9, v106
	v_mul_f32_e32 v102, 0xbfb8aa3b, v102
	v_exp_f32_e32 v102, v102
	v_sub_f32_e32 v79, 1.0, v79
	v_max_f32_e32 v79, 0, v79
	v_sqrt_f32_e32 v80, v79
	v_add_f32_e32 v79, v14, v111
	v_lshlrev_b32_e32 v111, 16, v103
	v_add_f32_e32 v102, 1.0, v102
	v_rcp_f32_e32 v125, v102
	v_add_f32_e32 v102, v2, v111
	v_mul_f32_e32 v102, 0xbfb8aa3b, v102
	v_exp_f32_e32 v102, v102
	v_and_b32_e32 v103, 0xffff0000, v103
	v_exp_f32_e32 v119, v110
	v_lshlrev_b32_e32 v185, 16, v59
	v_add_f32_e32 v102, 1.0, v102
	v_rcp_f32_e32 v102, v102
	v_and_b32_e32 v186, 0xffff0000, v59
	v_and_b32_e32 v59, 0xffff0000, v36
	v_lshlrev_b32_e32 v191, 16, v55
	v_mul_f32_e32 v102, v131, v102
	v_mul_f32_e32 v106, 0x3fb8aa3b, v102
	v_add_f32_e32 v102, v102, v102
	v_mul_f32_e32 v102, 0x3fb8aa3b, v102
	v_exp_f32_e32 v102, v102
	v_exp_f32_e32 v112, v106
	v_and_b32_e32 v192, 0xffff0000, v55
	v_pk_mul_f32 v[98:99], v[100:101], v[98:99]
	v_sub_f32_e32 v102, 1.0, v102
	v_max_f32_e32 v102, 0, v102
	v_sqrt_f32_e32 v116, v102
	v_add_f32_e32 v102, v10, v113
	v_mul_f32_e32 v102, 0xbfb8aa3b, v102
	v_exp_f32_e32 v102, v102
	v_pk_mul_f32 v[32:33], v[32:33], v[94:95]
	v_pk_mul_f32 v[34:35], v[34:35], v[88:89]
	v_pk_mul_f32 v[32:33], v[32:33], v[118:119]
	v_add_f32_e32 v102, 1.0, v102
	v_rcp_f32_e32 v120, v102
	v_add_f32_e32 v102, v3, v103
	v_mul_f32_e32 v102, 0xbfb8aa3b, v102
	v_exp_f32_e32 v102, v102
	v_pk_mul_f32 v[16:17], v[16:17], v[82:83]
	v_mul_f32_e32 v79, 0xbfb8aa3b, v79
	v_exp_f32_e32 v79, v79
	v_add_f32_e32 v102, 1.0, v102
	v_rcp_f32_e32 v102, v102
	v_and_b32_e32 v81, 0xffff0000, v81
	v_add_f32_e32 v79, 1.0, v79
	v_rcp_f32_e32 v84, v79
	v_mul_f32_e32 v102, v132, v102
	v_mul_f32_e32 v103, 0x3fb8aa3b, v102
	v_add_f32_e32 v102, v102, v102
	v_mul_f32_e32 v102, 0x3fb8aa3b, v102
	v_exp_f32_e32 v102, v102
	v_exp_f32_e32 v113, v103
	v_add_f32_e32 v79, v7, v81
	v_mul_f32_e32 v79, 0xbfb8aa3b, v79
	v_sub_f32_e32 v102, 1.0, v102
	v_max_f32_e32 v102, 0, v102
	v_sqrt_f32_e32 v117, v102
	v_add_f32_e32 v102, v11, v107
	v_mul_f32_e32 v102, 0xbfb8aa3b, v102
	v_exp_f32_e32 v102, v102
	v_pk_mul_f32 v[34:35], v[34:35], v[112:113]
	v_and_b32_e32 v105, 0xffff0000, v105
	v_exp_f32_e32 v79, v79
	v_add_f32_e32 v102, 1.0, v102
	v_rcp_f32_e32 v121, v102
	v_add_f32_e32 v102, v4, v114
	v_mul_f32_e32 v102, 0xbfb8aa3b, v102
	v_exp_f32_e32 v102, v102
	v_add_f32_e32 v79, 1.0, v79
	v_rcp_f32_e32 v79, v79
	v_and_b32_e32 v85, 0xffff0000, v85
	v_add_f32_e32 v102, 1.0, v102
	v_rcp_f32_e32 v102, v102
	v_mul_f32_e32 v81, v144, v79
	v_mul_f32_e32 v79, 0x3fb8aa3b, v81
	v_add_f32_e32 v81, v81, v81
	v_mul_f32_e32 v102, v133, v102
	v_mul_f32_e32 v103, 0x3fb8aa3b, v102
	v_add_f32_e32 v102, v102, v102
	v_mul_f32_e32 v102, 0x3fb8aa3b, v102
	v_exp_f32_e32 v102, v102
	v_exp_f32_e32 v106, v103
	v_mul_f32_e32 v81, 0x3fb8aa3b, v81
	v_add_f32_e32 v85, v15, v85
	v_sub_f32_e32 v102, 1.0, v102
	v_max_f32_e32 v102, 0, v102
	v_sqrt_f32_e32 v110, v102
	v_add_f32_e32 v102, v12, v115
	v_mul_f32_e32 v102, 0xbfb8aa3b, v102
	v_exp_f32_e32 v102, v102
	v_exp_f32_e32 v81, v81
	v_mul_f32_e32 v85, 0xbfb8aa3b, v85
	v_and_b32_e32 v109, 0xffff0000, v109
	v_add_f32_e32 v102, 1.0, v102
	v_rcp_f32_e32 v114, v102
	v_add_f32_e32 v102, v5, v104
	v_mul_f32_e32 v102, 0xbfb8aa3b, v102
	v_exp_f32_e32 v102, v102
	v_exp_f32_e32 v85, v85
	v_add_f32_e32 v109, v15, v109
	v_mul_f32_e32 v109, 0xbfb8aa3b, v109
	v_add_f32_e32 v102, 1.0, v102
	v_rcp_f32_e32 v102, v102
	v_exp_f32_e32 v109, v109
	v_sub_f32_e32 v81, 1.0, v81
	v_max_f32_e32 v81, 0, v81
	v_mul_f32_e32 v102, v134, v102
	v_mul_f32_e32 v103, 0x3fb8aa3b, v102
	v_add_f32_e32 v102, v102, v102
	v_mul_f32_e32 v102, 0x3fb8aa3b, v102
	v_exp_f32_e32 v102, v102
	v_exp_f32_e32 v107, v103
	v_add_f32_e32 v85, 1.0, v85
	v_sqrt_f32_e32 v81, v81
	v_sub_f32_e32 v102, 1.0, v102
	v_max_f32_e32 v102, 0, v102
	v_sqrt_f32_e32 v111, v102
	v_add_f32_e32 v102, v13, v108
	v_mul_f32_e32 v102, 0xbfb8aa3b, v102
	v_exp_f32_e32 v102, v102
	v_pk_mul_f32 v[16:17], v[16:17], v[106:107]
	v_rcp_f32_e32 v85, v85
	v_add_f32_e32 v109, 1.0, v109
	v_add_f32_e32 v102, 1.0, v102
	v_rcp_f32_e32 v115, v102
	v_add_f32_e32 v102, v6, v136
	v_lshlrev_b32_e32 v136, 16, v64
	v_add_f32_e32 v63, v0, v136
	v_mul_f32_e32 v63, 0xbfb8aa3b, v63
	v_exp_f32_e32 v63, v63
	v_and_b32_e32 v64, 0xffff0000, v64
	v_mul_f32_e32 v102, 0xbfb8aa3b, v102
	v_exp_f32_e32 v102, v102
	v_add_f32_e32 v63, 1.0, v63
	v_rcp_f32_e32 v63, v63
	v_exp_f32_e32 v78, v78
	v_add_f32_e32 v102, 1.0, v102
	v_rcp_f32_e32 v102, v102
	v_mul_f32_e32 v63, v129, v63
	v_mul_f32_e32 v136, 0x3fb8aa3b, v63
	v_add_f32_e32 v63, v63, v63
	v_mul_f32_e32 v63, 0x3fb8aa3b, v63
	v_exp_f32_e32 v63, v63
	v_mul_f32_e32 v103, v135, v102
	v_mul_f32_e32 v102, 0x3fb8aa3b, v103
	v_add_f32_e32 v103, v103, v103
	v_sub_f32_e32 v63, 1.0, v63
	v_max_f32_e32 v63, 0, v63
	v_sqrt_f32_e32 v138, v63
	v_add_f32_e32 v63, v8, v66
	v_mul_f32_e32 v63, 0xbfb8aa3b, v63
	v_exp_f32_e32 v63, v63
	v_mul_f32_e32 v103, 0x3fb8aa3b, v103
	v_exp_f32_e32 v103, v103
	v_exp_f32_e32 v136, v136
	v_add_f32_e32 v63, 1.0, v63
	v_rcp_f32_e32 v146, v63
	v_add_f32_e32 v63, v1, v64
	v_mul_f32_e32 v63, 0xbfb8aa3b, v63
	v_exp_f32_e32 v63, v63
	v_sub_f32_e32 v103, 1.0, v103
	v_max_f32_e32 v103, 0, v103
	v_sqrt_f32_e32 v104, v103
	v_add_f32_e32 v63, 1.0, v63
	v_rcp_f32_e32 v63, v63
	v_add_f32_e32 v103, v14, v137
	v_mul_f32_e32 v103, 0xbfb8aa3b, v103
	v_exp_f32_e32 v103, v103
; __device__ __forceinline__ void unpack8(const u32x4 w, float (&f)[8]) { f[0] = bflo(w.x); f[1] = bfhi(w.x); f[2] = bflo(w.y); f[3] = bfhi(w.y); f[4] = bflo(w.z); f[5] = bfhi(w.z); f[6] = bflo(w.w); f[7] = bfhi(w.w); }
; __device__ __forceinline__ float sigmoidf_(float x) { return __builtin_amdgcn_rcpf(1.0f + __expf(-x)); }
; template <int FINAL>
; __device__ __forceinline__ void phase_lru(const Ctx& c, int p, int l) {
;     ...
;           for (int u = 0; u < 4; ++u) {
;             const size_t row = (size_t)(g.row0 + t4 + u); float x[8], rp[8], ip[8];
;             unpack8(rx[u], x); unpack8(rr[u], rp); unpack8(ri[u], ip);
; #pragma unroll
;             for (int j = 0; j < 8; ++j) { const float la = c1[j] * sigmoidf_(rp[j] + ba[j]), a = __expf(la), bt = __builtin_amdgcn_sqrtf(fmaxf(1.0f - __expf(2.0f * la), 0.f)) * sigmoidf_(ip[j] + bx[j]) * x[j];
;                 B[j] = a * B[j] + bt; A[j] *= a; x[j] = B[j]; }
	v_mul_f32_e32 v63, v130, v63
	v_mul_f32_e32 v64, 0x3fb8aa3b, v63
	v_add_f32_e32 v63, v63, v63
	v_mul_f32_e32 v63, 0x3fb8aa3b, v63
	v_exp_f32_e32 v63, v63
	v_exp_f32_e32 v137, v64
	v_add_f32_e32 v103, 1.0, v103
	v_rcp_f32_e32 v108, v103
	v_sub_f32_e32 v63, 1.0, v63
	v_max_f32_e32 v63, 0, v63
	v_sqrt_f32_e32 v139, v63
	v_mul_f32_e32 v63, 0x3fb8aa3b, v60
	v_add_f32_e32 v60, v60, v60
	v_mul_f32_e32 v60, 0x3fb8aa3b, v60
	v_exp_f32_e32 v60, v60
	v_exp_f32_e32 v148, v63
	v_pk_mul_f32 v[32:33], v[32:33], v[136:137]
	v_add_f32_e32 v103, v7, v105
	v_sub_f32_e32 v60, 1.0, v60
	v_max_f32_e32 v60, 0, v60
	v_sqrt_f32_e32 v150, v60
	v_add_f32_e32 v60, v10, v67
	v_mul_f32_e32 v60, 0xbfb8aa3b, v60
	v_exp_f32_e32 v60, v60
	v_mul_f32_e32 v103, 0xbfb8aa3b, v103
	v_exp_f32_e32 v103, v103
	v_exp_f32_e32 v79, v79
	v_add_f32_e32 v60, 1.0, v60
	v_rcp_f32_e32 v152, v60
	v_add_f32_e32 v60, v3, v65
	v_mul_f32_e32 v60, 0xbfb8aa3b, v60
	v_exp_f32_e32 v60, v60
	v_add_f32_e32 v65, v15, v161
	v_lshlrev_b32_e32 v161, 16, v58
	v_lshlrev_b32_e32 v58, 16, v36
	v_add_f32_e32 v60, 1.0, v60
	v_rcp_f32_e32 v60, v60
	v_pk_mul_f32 v[58:59], v[98:99], v[58:59]
	v_pk_mul_f32 v[98:99], v[124:125], v[122:123]
	v_pk_fma_f32 v[20:21], v[20:21], v[94:95], v[58:59]
	v_mul_f32_e32 v60, v132, v60
	v_mul_f32_e32 v63, 0x3fb8aa3b, v60
	v_add_f32_e32 v60, v60, v60
	v_mul_f32_e32 v60, 0x3fb8aa3b, v60
	v_exp_f32_e32 v60, v60
	v_lshlrev_b32_e32 v58, 16, v40
	v_and_b32_e32 v59, 0xffff0000, v40
	v_pk_mul_f32 v[58:59], v[98:99], v[58:59]
	v_sub_f32_e32 v60, 1.0, v60
	v_max_f32_e32 v60, 0, v60
	v_sqrt_f32_e32 v151, v60
	v_add_f32_e32 v60, v11, v61
	v_mul_f32_e32 v60, 0xbfb8aa3b, v60
	v_exp_f32_e32 v60, v60
	v_pk_fma_f32 v[20:21], v[118:119], v[20:21], v[58:59]
	v_lshlrev_b32_e32 v58, 16, v44
	v_and_b32_e32 v59, 0xffff0000, v44
	v_add_f32_e32 v60, 1.0, v60
	v_rcp_f32_e32 v153, v60
	v_add_f32_e32 v60, v4, v154
	v_mul_f32_e32 v60, 0xbfb8aa3b, v60
	v_exp_f32_e32 v60, v60
	v_pk_mul_f32 v[98:99], v[146:147], v[138:139]
	v_exp_f32_e32 v149, v63
	v_pk_mul_f32 v[58:59], v[98:99], v[58:59]
	v_add_f32_e32 v60, 1.0, v60
	v_rcp_f32_e32 v60, v60
	v_pk_fma_f32 v[20:21], v[136:137], v[20:21], v[58:59]
	v_lshlrev_b32_e32 v58, 16, v48
	v_and_b32_e32 v59, 0xffff0000, v48
	v_mul_f32_e32 v60, v133, v60
	v_mul_f32_e32 v61, 0x3fb8aa3b, v60
	v_add_f32_e32 v60, v60, v60
	v_mul_f32_e32 v60, 0x3fb8aa3b, v60
	v_exp_f32_e32 v60, v60
	v_exp_f32_e32 v66, v61
	v_pk_mul_f32 v[34:35], v[34:35], v[148:149]
	v_lshlrev_b32_e32 v48, 16, v38
	v_sub_f32_e32 v60, 1.0, v60
	v_max_f32_e32 v60, 0, v60
	v_sqrt_f32_e32 v154, v60
	v_add_f32_e32 v60, v12, v156
	v_mul_f32_e32 v60, 0xbfb8aa3b, v60
	v_exp_f32_e32 v60, v60
	v_add_f32_e32 v103, 1.0, v103
	v_rcp_f32_e32 v103, v103
	v_mul_f32_e32 v65, 0xbfb8aa3b, v65
	v_add_f32_e32 v60, 1.0, v60
	v_rcp_f32_e32 v156, v60
	v_add_f32_e32 v60, v5, v155
	v_mul_f32_e32 v60, 0xbfb8aa3b, v60
	v_exp_f32_e32 v60, v60
	v_mul_f32_e32 v105, v144, v103
	v_mul_f32_e32 v103, 0x3fb8aa3b, v105
	v_add_f32_e32 v105, v105, v105
	v_add_f32_e32 v60, 1.0, v60
	v_rcp_f32_e32 v60, v60
	v_mul_f32_e32 v105, 0x3fb8aa3b, v105
	v_exp_f32_e32 v105, v105
	v_exp_f32_e32 v65, v65
	v_mul_f32_e32 v60, v134, v60
	v_mul_f32_e32 v61, 0x3fb8aa3b, v60
	v_add_f32_e32 v60, v60, v60
	v_mul_f32_e32 v60, 0x3fb8aa3b, v60
	v_exp_f32_e32 v60, v60
	v_exp_f32_e32 v67, v61
	v_sub_f32_e32 v105, 1.0, v105
	v_max_f32_e32 v105, 0, v105
	v_sub_f32_e32 v60, 1.0, v60
	v_max_f32_e32 v60, 0, v60
	v_sqrt_f32_e32 v155, v60
	v_add_f32_e32 v60, v13, v62
	v_mul_f32_e32 v60, 0xbfb8aa3b, v60
	v_exp_f32_e32 v60, v60
	v_pk_mul_f32 v[16:17], v[16:17], v[66:67]
	v_sqrt_f32_e32 v105, v105
	v_rcp_f32_e32 v109, v109
	v_add_f32_e32 v60, 1.0, v60
	v_rcp_f32_e32 v157, v60
	v_add_f32_e32 v60, v6, v158
	v_mul_f32_e32 v60, 0xbfb8aa3b, v60
	v_exp_f32_e32 v60, v60
	v_and_b32_e32 v158, 0xffff0000, v56
	v_lshlrev_b32_e32 v56, 16, v52
	v_add_f32_e32 v65, 1.0, v65
	v_add_f32_e32 v60, 1.0, v60
	v_rcp_f32_e32 v60, v60
	v_exp_f32_e32 v102, v102
	v_exp_f32_e32 v103, v103
	v_rcp_f32_e32 v65, v65
	v_mul_f32_e32 v61, v135, v60
	v_mul_f32_e32 v60, 0x3fb8aa3b, v61
	v_add_f32_e32 v61, v61, v61
	v_mul_f32_e32 v61, 0x3fb8aa3b, v61
	v_exp_f32_e32 v61, v61
	v_exp_f32_e32 v60, v60
	v_pk_mul_f32 v[18:19], v[18:19], v[78:79]
	v_sub_f32_e32 v61, 1.0, v61
	v_max_f32_e32 v61, 0, v61
	v_sqrt_f32_e32 v62, v61
	v_add_f32_e32 v61, v14, v160
	v_mul_f32_e32 v61, 0xbfb8aa3b, v61
	v_exp_f32_e32 v61, v61
	v_and_b32_e32 v160, 0xffff0000, v57
	v_pk_mul_f32 v[18:19], v[18:19], v[102:103]
	v_add_f32_e32 v61, 1.0, v61
	v_rcp_f32_e32 v64, v61
	v_add_f32_e32 v61, v7, v159
	v_lshlrev_b32_e32 v159, 16, v57
	v_and_b32_e32 v57, 0xffff0000, v52
	v_add_f32_e32 v52, v0, v145
	v_mul_f32_e32 v52, 0xbfb8aa3b, v52
	v_exp_f32_e32 v52, v52
	v_add_f32_e32 v36, v2, v159
	v_mul_f32_e32 v36, 0xbfb8aa3b, v36
	v_exp_f32_e32 v36, v36
	v_add_f32_e32 v52, 1.0, v52
	v_rcp_f32_e32 v52, v52
	v_add_f32_e32 v57, v9, v57
	v_add_f32_e32 v36, 1.0, v36
	v_rcp_f32_e32 v36, v36
	v_mul_f32_e32 v53, v129, v52
	v_mul_f32_e32 v52, 0x3fb8aa3b, v53
	v_add_f32_e32 v53, v53, v53
	v_mul_f32_e32 v53, 0x3fb8aa3b, v53
	v_exp_f32_e32 v53, v53
	v_mul_f32_e32 v57, 0xbfb8aa3b, v57
	v_exp_f32_e32 v57, v57
	v_mul_f32_e32 v36, v131, v36
	v_sub_f32_e32 v53, 1.0, v53
	v_max_f32_e32 v53, 0, v53
	v_sqrt_f32_e32 v54, v53
	v_add_f32_e32 v53, v8, v56
	v_mul_f32_e32 v53, 0xbfb8aa3b, v53
	v_exp_f32_e32 v53, v53
	v_mul_f32_e32 v40, 0x3fb8aa3b, v36
	v_add_f32_e32 v36, v36, v36
	v_add_f32_e32 v57, 1.0, v57
	v_add_f32_e32 v53, 1.0, v53
	v_rcp_f32_e32 v56, v53
	v_add_f32_e32 v53, v1, v158
	v_mul_f32_e32 v53, 0xbfb8aa3b, v53
	v_exp_f32_e32 v53, v53
	v_mul_f32_e32 v36, 0x3fb8aa3b, v36
; __device__ __forceinline__ void unpack8(const u32x4 w, float (&f)[8]) { f[0] = bflo(w.x); f[1] = bfhi(w.x); f[2] = bflo(w.y); f[3] = bfhi(w.y); f[4] = bflo(w.z); f[5] = bfhi(w.z); f[6] = bflo(w.w); f[7] = bfhi(w.w); }
; __device__ __forceinline__ float sigmoidf_(float x) { return __builtin_amdgcn_rcpf(1.0f + __expf(-x)); }
; template <int FINAL>
; __device__ __forceinline__ void phase_lru(const Ctx& c, int p, int l) {
;     ...
;         for (int t4 = 0; t4 < g.n; t4 += 4) {
;           u32x4 rx[4], rr[4], ri[4];
; #pragma unroll
;           for (int u = 0; u < 4; ++u) { const size_t row = (size_t)(g.row0 + t4 + u); rx[u] = *(const u32x4*)(Z + row * ZW + C_LRU + ch); rr[u] = *(const u32x4*)(T + row * 2048 + ch); ri[u] = *(const u32x4*)(T + row * 2048 + 1024 + ch); }
; #pragma unroll
;           for (int u = 0; u < 4; ++u) {
;             const size_t row = (size_t)(g.row0 + t4 + u); float x[8], rp[8], ip[8];
;             unpack8(rx[u], x); unpack8(rr[u], rp); unpack8(ri[u], ip);
; #pragma unroll
;             for (int j = 0; j < 8; ++j) { const float la = c1[j] * sigmoidf_(rp[j] + ba[j]), a = __expf(la), bt = __builtin_amdgcn_sqrtf(fmaxf(1.0f - __expf(2.0f * la), 0.f)) * sigmoidf_(ip[j] + bx[j]) * x[j];
;                 B[j] = a * B[j] + bt; A[j] *= a; x[j] = B[j]; }
	v_rcp_f32_e32 v57, v57
	v_exp_f32_e32 v36, v36
	v_add_f32_e32 v53, 1.0, v53
	v_rcp_f32_e32 v53, v53
	v_exp_f32_e32 v52, v52
	v_sub_f32_e32 v36, 1.0, v36
	v_max_f32_e32 v36, 0, v36
	v_mul_f32_e32 v55, v130, v53
	v_mul_f32_e32 v53, 0x3fb8aa3b, v55
	v_add_f32_e32 v55, v55, v55
	v_mul_f32_e32 v55, 0x3fb8aa3b, v55
	v_exp_f32_e32 v55, v55
	v_exp_f32_e32 v53, v53
	v_mul_f32_e32 v61, 0xbfb8aa3b, v61
	v_exp_f32_e32 v61, v61
	v_sub_f32_e32 v55, 1.0, v55
	v_max_f32_e32 v55, 0, v55
	v_sqrt_f32_e32 v55, v55
	v_pk_mul_f32 v[32:33], v[32:33], v[52:53]
	v_add_f32_e32 v61, 1.0, v61
	v_rcp_f32_e32 v61, v61
	v_pk_mul_f32 v[54:55], v[56:57], v[54:55]
	v_mul_f32_e32 v63, v144, v61
	v_pk_mul_f32 v[54:55], v[54:55], v[58:59]
	v_pk_mul_f32 v[58:59], v[96:97], v[92:93]
	v_pk_fma_f32 v[20:21], v[52:53], v[20:21], v[54:55]
	v_sqrt_f32_e32 v54, v36
	v_add_f32_e32 v36, v10, v187
	v_mul_f32_e32 v36, 0xbfb8aa3b, v36
	v_exp_f32_e32 v36, v36
	v_exp_f32_e32 v52, v40
	v_mul_f32_e32 v61, 0x3fb8aa3b, v63
	v_add_f32_e32 v63, v63, v63
	v_add_f32_e32 v36, 1.0, v36
	v_rcp_f32_e32 v56, v36
	v_add_f32_e32 v36, v3, v160
	v_mul_f32_e32 v36, 0xbfb8aa3b, v36
	v_exp_f32_e32 v36, v36
	v_mul_f32_e32 v63, 0x3fb8aa3b, v63
	v_exp_f32_e32 v63, v63
	v_exp_f32_e32 v61, v61
	v_add_f32_e32 v36, 1.0, v36
	v_rcp_f32_e32 v36, v36
	v_sub_f32_e32 v63, 1.0, v63
	v_max_f32_e32 v63, 0, v63
	v_sqrt_f32_e32 v63, v63
	v_mul_f32_e32 v36, v132, v36
	v_mul_f32_e32 v40, 0x3fb8aa3b, v36
	v_add_f32_e32 v36, v36, v36
	v_mul_f32_e32 v36, 0x3fb8aa3b, v36
	v_exp_f32_e32 v36, v36
	v_exp_f32_e32 v53, v40
	v_pk_mul_f32 v[18:19], v[18:19], v[60:61]
	v_sub_f32_e32 v36, 1.0, v36
	v_max_f32_e32 v36, 0, v36
	v_sqrt_f32_e32 v55, v36
	v_add_f32_e32 v36, v11, v188
	v_mul_f32_e32 v36, 0xbfb8aa3b, v36
	v_exp_f32_e32 v36, v36
	v_pk_mul_f32 v[34:35], v[34:35], v[52:53]
	v_add_f32_e32 v36, 1.0, v36
	v_rcp_f32_e32 v57, v36
	v_lshlrev_b32_e32 v36, 16, v37
	v_and_b32_e32 v37, 0xffff0000, v37
	v_pk_mul_f32 v[36:37], v[58:59], v[36:37]
	s_nop 0
	v_pk_fma_f32 v[22:23], v[22:23], v[88:89], v[36:37]
	v_lshlrev_b32_e32 v36, 16, v41
	v_and_b32_e32 v37, 0xffff0000, v41
	v_pk_mul_f32 v[40:41], v[120:121], v[116:117]
	s_nop 0
	v_pk_mul_f32 v[36:37], v[40:41], v[36:37]
	v_pk_mul_f32 v[40:41], v[152:153], v[150:151]
	v_pk_fma_f32 v[22:23], v[112:113], v[22:23], v[36:37]
	v_lshlrev_b32_e32 v36, 16, v45
	v_and_b32_e32 v37, 0xffff0000, v45
	v_pk_mul_f32 v[36:37], v[40:41], v[36:37]
	v_pk_mul_f32 v[40:41], v[56:57], v[54:55]
	v_pk_fma_f32 v[22:23], v[148:149], v[22:23], v[36:37]
	v_lshlrev_b32_e32 v36, 16, v49
	v_and_b32_e32 v37, 0xffff0000, v49
	v_pk_mul_f32 v[36:37], v[40:41], v[36:37]
	v_add_f32_e32 v45, v13, v190
	v_pk_fma_f32 v[22:23], v[52:53], v[22:23], v[36:37]
	v_add_f32_e32 v36, v4, v161
	v_mul_f32_e32 v36, 0xbfb8aa3b, v36
	v_exp_f32_e32 v36, v36
	v_mul_f32_e32 v45, 0xbfb8aa3b, v45
	v_exp_f32_e32 v45, v45
	v_and_b32_e32 v49, 0xffff0000, v38
	v_add_f32_e32 v36, 1.0, v36
	v_rcp_f32_e32 v36, v36
	v_pk_mul_f32 v[52:53], v[90:91], v[86:87]
	v_add_f32_e32 v45, 1.0, v45
	v_pk_mul_f32 v[48:49], v[52:53], v[48:49]
	v_mul_f32_e32 v37, v133, v36
	v_mul_f32_e32 v36, 0x3fb8aa3b, v37
	v_add_f32_e32 v37, v37, v37
	v_mul_f32_e32 v37, 0x3fb8aa3b, v37
	v_exp_f32_e32 v37, v37
	v_rcp_f32_e32 v45, v45
	v_pk_fma_f32 v[24:25], v[24:25], v[82:83], v[48:49]
	v_lshlrev_b32_e32 v48, 16, v42
	v_sub_f32_e32 v37, 1.0, v37
	v_max_f32_e32 v37, 0, v37
	v_sqrt_f32_e32 v40, v37
	v_add_f32_e32 v37, v12, v189
	v_mul_f32_e32 v37, 0xbfb8aa3b, v37
	v_exp_f32_e32 v37, v37
	v_and_b32_e32 v49, 0xffff0000, v42
	v_pk_mul_f32 v[52:53], v[114:115], v[110:111]
	v_exp_f32_e32 v36, v36
	v_add_f32_e32 v37, 1.0, v37
	v_rcp_f32_e32 v44, v37
	v_add_f32_e32 v37, v5, v184
	v_mul_f32_e32 v37, 0xbfb8aa3b, v37
	v_exp_f32_e32 v37, v37
	v_pk_mul_f32 v[48:49], v[52:53], v[48:49]
	v_pk_mul_f32 v[52:53], v[156:157], v[154:155]
	v_pk_fma_f32 v[24:25], v[106:107], v[24:25], v[48:49]
	v_add_f32_e32 v37, 1.0, v37
	v_rcp_f32_e32 v37, v37
	v_lshlrev_b32_e32 v48, 16, v46
	v_and_b32_e32 v49, 0xffff0000, v46
	v_pk_mul_f32 v[48:49], v[52:53], v[48:49]
	v_mul_f32_e32 v41, v134, v37
	v_mul_f32_e32 v37, 0x3fb8aa3b, v41
	v_add_f32_e32 v41, v41, v41
	v_mul_f32_e32 v41, 0x3fb8aa3b, v41
	v_exp_f32_e32 v41, v41
	v_exp_f32_e32 v37, v37
	v_pk_fma_f32 v[24:25], v[66:67], v[24:25], v[48:49]
	v_lshlrev_b32_e32 v48, 16, v50
	v_sub_f32_e32 v41, 1.0, v41
	v_max_f32_e32 v41, 0, v41
	v_sqrt_f32_e32 v41, v41
	v_and_b32_e32 v49, 0xffff0000, v50
	v_pk_mul_f32 v[16:17], v[16:17], v[36:37]
	v_pk_mul_f32 v[40:41], v[44:45], v[40:41]
	s_nop 0
	v_pk_mul_f32 v[40:41], v[40:41], v[48:49]
	v_pk_mul_f32 v[48:49], v[84:85], v[80:81]
	v_pk_fma_f32 v[24:25], v[36:37], v[24:25], v[40:41]
	v_add_f32_e32 v36, v6, v185
	v_mul_f32_e32 v36, 0xbfb8aa3b, v36
	v_exp_f32_e32 v36, v36
	s_nop 0
	v_add_f32_e32 v36, 1.0, v36
	v_rcp_f32_e32 v36, v36
	s_nop 0
	v_mul_f32_e32 v37, v135, v36
	v_mul_f32_e32 v36, 0x3fb8aa3b, v37
	v_add_f32_e32 v37, v37, v37
	v_mul_f32_e32 v37, 0x3fb8aa3b, v37
	v_exp_f32_e32 v37, v37
	v_exp_f32_e32 v36, v36
	v_sub_f32_e32 v37, 1.0, v37
	v_max_f32_e32 v37, 0, v37
	v_sqrt_f32_e32 v40, v37
	v_add_f32_e32 v37, v14, v191
	v_mul_f32_e32 v37, 0xbfb8aa3b, v37
	v_exp_f32_e32 v37, v37
	s_nop 0
	v_add_f32_e32 v37, 1.0, v37
	v_rcp_f32_e32 v44, v37
	v_add_f32_e32 v37, v7, v186
	v_mul_f32_e32 v37, 0xbfb8aa3b, v37
	v_exp_f32_e32 v37, v37
	s_nop 0
	v_add_f32_e32 v37, 1.0, v37
	v_rcp_f32_e32 v37, v37
	s_nop 0
	v_mul_f32_e32 v38, v144, v37
	v_mul_f32_e32 v37, 0x3fb8aa3b, v38
	v_add_f32_e32 v38, v38, v38
	v_mul_f32_e32 v38, 0x3fb8aa3b, v38
	v_exp_f32_e32 v38, v38
	v_exp_f32_e32 v37, v37
	v_sub_f32_e32 v38, 1.0, v38
	v_max_f32_e32 v38, 0, v38
	v_sqrt_f32_e32 v41, v38
	v_add_f32_e32 v38, v15, v192
	v_mul_f32_e32 v38, 0xbfb8aa3b, v38
	v_exp_f32_e32 v38, v38
	v_pk_mul_f32 v[18:19], v[18:19], v[36:37]
	v_add_f32_e32 v38, 1.0, v38
	v_rcp_f32_e32 v45, v38
	v_lshlrev_b32_e32 v38, 16, v39
	v_and_b32_e32 v39, 0xffff0000, v39
	v_pk_mul_f32 v[38:39], v[48:49], v[38:39]
	v_pk_mul_f32 v[40:41], v[44:45], v[40:41]
	v_pk_fma_f32 v[26:27], v[26:27], v[78:79], v[38:39]
	v_lshlrev_b32_e32 v38, 16, v43
	v_and_b32_e32 v39, 0xffff0000, v43
	v_pk_mul_f32 v[42:43], v[108:109], v[104:105]
	s_nop 0
	v_pk_mul_f32 v[38:39], v[42:43], v[38:39]
	v_pk_mul_f32 v[42:43], v[64:65], v[62:63]
	v_pk_fma_f32 v[26:27], v[102:103], v[26:27], v[38:39]
	v_lshlrev_b32_e32 v38, 16, v47
	v_and_b32_e32 v39, 0xffff0000, v47
	v_pk_mul_f32 v[38:39], v[42:43], v[38:39]
	s_nop 0
	v_pk_fma_f32 v[26:27], v[60:61], v[26:27], v[38:39]
	v_lshlrev_b32_e32 v38, 16, v51
	v_and_b32_e32 v39, 0xffff0000, v51
	v_pk_mul_f32 v[38:39], v[40:41], v[38:39]
	s_nop 0
	v_pk_fma_f32 v[26:27], v[36:37], v[26:27], v[38:39]
	s_andn2_b64 exec, exec, s[2:3]
	s_cbranch_execnz .LBB0_1077
; template <int FINAL>
; __device__ __forceinline__ void phase_lru(const Ctx& c, int p, int l) {
;     ...
;         if (!FINAL) { float* ca = car + (size_t)s * 2048 + ch;
; #pragma unroll
;             for (int j = 0; j < 8; ++j) { ca[j] = A[j]; ca[1024 + j] = B[j]; } }
	s_waitcnt vmcnt(0)
	s_or_b64 exec, exec, s[2:3]
	v_ashrrev_i32_e32 v73, 31, v72
	v_lshlrev_b64 v[0:1], 13, v[72:73]
	v_lshl_add_u64 v[0:1], s[6:7], 0, v[0:1]
	v_lshlrev_b32_e32 v30, 2, v128
	v_lshl_add_u64 v[0:1], v[0:1], 0, v[30:31]
	v_add_co_u32_e32 v2, vcc, 0x1000, v0
	v_add_u32_e32 v126, s11, v126
	s_nop 0
	v_addc_co_u32_e32 v3, vcc, 0, v1, vcc
	v_cmp_le_i32_e32 vcc, s10, v126
	s_or_b64 s[8:9], vcc, s[8:9]
	v_add_u32_e32 v127, s14, v127
	global_store_dwordx4 v[0:1], v[32:35], off
	global_store_dwordx4 v[2:3], v[20:23], off
	global_store_dwordx4 v[0:1], v[16:19], off offset:16
	global_store_dwordx4 v[2:3], v[24:27], off offset:16
	s_andn2_b64 exec, exec, s[8:9]
	s_cbranch_execnz .LBB0_1072

; __device__ __forceinline__ float softplusf_(float x) { return fmaxf(x, 0.f) + __logf(1.0f + __expf(-fabsf(x))); }
; __device__ __forceinline__ Seq seq_of(int p, int q) { Seq s; if (q < 2) { s.row0 = q * SEQ; s.T = SEQ; s.sample = 0; s.b = 2 * p + q; } else { s.row0 = 16384 + (q - 2) * DSEQ; s.T = DSEQ; s.sample = 1; s.b = q - 2; } return s; }
; __device__ __forceinline__ Seg seg_of(int s) { Seg g; if (s < 256) { g.q = s >> 7; g.c = s & 127; g.row0 = g.q * SEQ + g.c * 64; g.n = 64; g.nch = 128; } else { g.q = 2 + (s - 256); g.c = 0; g.row0 = 16384 + (s - 256) * DSEQ; g.n = DSEQ; g.nch = 1; } return g; }
; template <int FINAL>
; __device__ __forceinline__ void phase_lru(const Ctx& c, int p, int l) {
;     ...
;         const int s = i >> 7, ch = 8 * (i & 127); const Seg g = seg_of(s); const Seq sq = seq_of(p, g.q);
;         float ba[8], bx[8], c1[8], A[8], B[8];
; #pragma unroll
;         for (int j = 0; j < 8; ++j) { ba[j] = inp(c, I_LBA)[(size_t)l * D + ch + j]; bx[j] = inp(c, I_LBX)[(size_t)l * D + ch + j]; c1[j] = -8.0f * softplusf_(-inp(c, I_LLAM)[(size_t)l * D + ch + j]); A[j] = 1.f; B[j] = 0.f; }
;         if (FINAL) {
;             if (sq.sample) {
; #pragma unroll
;                 for (int j = 0; j < 8; ++j) B[j] = inp(c, I_SLRU)[((size_t)l * DB + sq.b) * D + ch + j]; }
;             for (int cp = 0; cp < g.c; ++cp) { const float* ca = car + (size_t)(s - g.c + cp) * 2048 + ch;
; #pragma unroll
;                 for (int j = 0; j < 8; ++j) B[j] = ca[j] * B[j] + ca[1024 + j]; }
;         }
;         for (int t4 = 0; t4 < g.n; t4 += 4) {
;           u32x4 rx[4], rr[4], ri[4];
; #pragma unroll
;           for (int u = 0; u < 4; ++u) { const size_t row = (size_t)(g.row0 + t4 + u); rx[u] = *(const u32x4*)(Z + row * ZW + C_LRU + ch); rr[u] = *(const u32x4*)(T + row * 2048 + ch); ri[u] = *(const u32x4*)(T + row * 2048 + 1024 + ch); }
.LBB0_1142:
	s_andn2_saveexec_b64 s[4:5], s[4:5]
	s_or_b64 exec, exec, s[4:5]
	s_mov_b32 s0, 0xbfb8aa3b
	s_waitcnt vmcnt(0)
	v_mul_f32_e64 v30, |v38|, s0
	v_exp_f32_e32 v30, v30
	s_mov_b32 s15, 0x800000
	s_mov_b32 s16, 0x3f317217
	s_mov_b32 s17, 0x7f800000
	v_add_f32_e32 v30, 1.0, v30
	v_cmp_gt_f32_e32 vcc, s15, v30
	v_max_f32_e64 v32, -v38, -v38
	v_max_f32_e32 v32, 0, v32
	v_cndmask_b32_e64 v33, 0, 32, vcc
	v_ldexp_f32 v30, v30, v33
	v_log_f32_e32 v30, v30
	v_mul_f32_e64 v33, |v39|, s0
	v_exp_f32_e32 v33, v33
	v_ashrrev_i32_e32 v43, 31, v42
	v_mul_f32_e32 v34, 0x3f317217, v30
	v_fma_f32 v34, v30, s16, -v34
	v_fmac_f32_e32 v34, 0x3377d1cf, v30
	v_fmac_f32_e32 v34, 0x3f317217, v30
	v_cmp_lt_f32_e64 s[4:5], |v30|, s17
	s_mov_b32 s14, 0
	s_mov_b64 s[24:25], 0x10800
	v_cndmask_b32_e64 v30, v30, v34, s[4:5]
	v_cndmask_b32_e32 v34, 0, v178, vcc
	v_sub_f32_e32 v30, v30, v34
	v_add_f32_e32 v30, v32, v30
	v_add_f32_e32 v32, 1.0, v33
	v_cmp_gt_f32_e32 vcc, s15, v32
	v_mul_f32_e32 v130, 0xc1000000, v30
	v_max_f32_e64 v30, -v39, -v39
	v_cndmask_b32_e64 v33, 0, 32, vcc
	v_ldexp_f32 v32, v32, v33
	v_log_f32_e32 v32, v32
	v_cndmask_b32_e32 v34, 0, v178, vcc
	v_max_f32_e32 v30, 0, v30
	v_mul_f32_e32 v33, 0x3f317217, v32
	v_fma_f32 v33, v32, s16, -v33
	v_fmac_f32_e32 v33, 0x3377d1cf, v32
	v_fmac_f32_e32 v33, 0x3f317217, v32
	v_cmp_lt_f32_e64 s[4:5], |v32|, s17
	s_nop 1
	v_cndmask_b32_e64 v32, v32, v33, s[4:5]
	v_mul_f32_e64 v33, |v40|, s0
	v_exp_f32_e32 v33, v33
	v_sub_f32_e32 v32, v32, v34
	v_add_f32_e32 v30, v30, v32
	v_mul_f32_e32 v131, 0xc1000000, v30
	v_add_f32_e32 v32, 1.0, v33
	v_cmp_gt_f32_e32 vcc, s15, v32
	v_max_f32_e64 v30, -v40, -v40
	v_max_f32_e32 v30, 0, v30
	v_cndmask_b32_e64 v33, 0, 32, vcc
	v_ldexp_f32 v32, v32, v33
	v_log_f32_e32 v32, v32
	v_cndmask_b32_e32 v34, 0, v178, vcc
	v_mul_f32_e32 v33, 0x3f317217, v32
	v_fma_f32 v33, v32, s16, -v33
	v_fmac_f32_e32 v33, 0x3377d1cf, v32
	v_fmac_f32_e32 v33, 0x3f317217, v32
	v_cmp_lt_f32_e64 s[4:5], |v32|, s17
	s_nop 1
	v_cndmask_b32_e64 v32, v32, v33, s[4:5]
	v_mul_f32_e64 v33, |v41|, s0
	v_exp_f32_e32 v33, v33
	v_sub_f32_e32 v32, v32, v34
	v_add_f32_e32 v30, v30, v32
	v_mul_f32_e32 v132, 0xc1000000, v30
	v_add_f32_e32 v32, 1.0, v33
	v_cmp_gt_f32_e32 vcc, s15, v32
	v_max_f32_e64 v30, -v41, -v41
	v_max_f32_e32 v30, 0, v30
	v_cndmask_b32_e64 v33, 0, 32, vcc
	v_ldexp_f32 v32, v32, v33
	v_log_f32_e32 v32, v32
	v_cndmask_b32_e32 v34, 0, v178, vcc
	v_mul_f32_e32 v33, 0x3f317217, v32
	v_fma_f32 v33, v32, s16, -v33
	v_fmac_f32_e32 v33, 0x3377d1cf, v32
	v_fmac_f32_e32 v33, 0x3f317217, v32
	v_cmp_lt_f32_e64 s[4:5], |v32|, s17
	s_nop 1
	v_cndmask_b32_e64 v32, v32, v33, s[4:5]
	v_mul_f32_e64 v33, |v24|, s0
	v_exp_f32_e32 v33, v33
	v_sub_f32_e32 v32, v32, v34
	v_add_f32_e32 v30, v30, v32
	v_mul_f32_e32 v133, 0xc1000000, v30
	v_add_f32_e32 v32, 1.0, v33
	v_cmp_gt_f32_e32 vcc, s15, v32
	v_max_f32_e64 v24, -v24, -v24
	v_max_f32_e32 v24, 0, v24
	v_cndmask_b32_e64 v33, 0, 32, vcc
	v_ldexp_f32 v32, v32, v33
	v_log_f32_e32 v32, v32
	v_cndmask_b32_e32 v33, 0, v178, vcc
	v_mul_f32_e32 v30, 0x3f317217, v32
	v_fma_f32 v30, v32, s16, -v30
	v_fmac_f32_e32 v30, 0x3377d1cf, v32
	v_fmac_f32_e32 v30, 0x3f317217, v32
	v_cmp_lt_f32_e64 s[4:5], |v32|, s17
	s_nop 1
	v_cndmask_b32_e64 v30, v32, v30, s[4:5]
	v_mul_f32_e64 v32, |v25|, s0
	v_exp_f32_e32 v32, v32
	v_sub_f32_e32 v30, v30, v33
	v_add_f32_e32 v24, v24, v30
	v_mul_f32_e32 v134, 0xc1000000, v24
	v_add_f32_e32 v30, 1.0, v32
	v_cmp_gt_f32_e32 vcc, s15, v30
	v_max_f32_e64 v24, -v25, -v25
	v_max_f32_e32 v24, 0, v24
	v_cndmask_b32_e64 v32, 0, 32, vcc
	v_ldexp_f32 v30, v30, v32
	v_log_f32_e32 v30, v30
	v_cndmask_b32_e32 v32, 0, v178, vcc
	v_mul_f32_e32 v25, 0x3f317217, v30
	v_fma_f32 v25, v30, s16, -v25
	v_fmac_f32_e32 v25, 0x3377d1cf, v30
	v_fmac_f32_e32 v25, 0x3f317217, v30
	v_cmp_lt_f32_e64 s[4:5], |v30|, s17
	s_nop 1
	v_cndmask_b32_e64 v25, v30, v25, s[4:5]
	v_mul_f32_e64 v30, |v26|, s0
	v_exp_f32_e32 v30, v30
	v_sub_f32_e32 v25, v25, v32
	v_add_f32_e32 v24, v24, v25
	v_mul_f32_e32 v135, 0xc1000000, v24
	v_add_f32_e32 v25, 1.0, v30
	v_cmp_gt_f32_e32 vcc, s15, v25
	v_max_f32_e64 v24, -v26, -v26
	v_max_f32_e32 v24, 0, v24
	v_cndmask_b32_e64 v30, 0, 32, vcc
	v_ldexp_f32 v25, v25, v30
	v_log_f32_e32 v25, v25
	v_cndmask_b32_e32 v30, 0, v178, vcc
	v_mul_f32_e32 v26, 0x3f317217, v25
	v_fma_f32 v26, v25, s16, -v26
	v_fmac_f32_e32 v26, 0x3377d1cf, v25
	v_fmac_f32_e32 v26, 0x3f317217, v25
	v_cmp_lt_f32_e64 s[4:5], |v25|, s17
	s_nop 1
	v_cndmask_b32_e64 v25, v25, v26, s[4:5]
	v_mul_f32_e64 v26, |v27|, s0
	v_exp_f32_e32 v26, v26
	v_sub_f32_e32 v25, v25, v30
	v_add_f32_e32 v24, v24, v25
	v_mul_f32_e32 v144, 0xc1000000, v24
	v_add_f32_e32 v25, 1.0, v26
	v_cmp_gt_f32_e32 vcc, s15, v25
	v_max_f32_e64 v24, -v27, -v27
	v_max_f32_e32 v24, 0, v24
	v_cndmask_b32_e64 v26, 0, 32, vcc
	v_ldexp_f32 v25, v25, v26
	v_log_f32_e32 v25, v25
	v_lshlrev_b32_e32 v30, 1, v64
	v_mul_f32_e32 v26, 0x3f317217, v25
	v_fma_f32 v26, v25, s16, -v26
	v_fmac_f32_e32 v26, 0x3377d1cf, v25
	v_fmac_f32_e32 v26, 0x3f317217, v25
	v_cmp_lt_f32_e64 s[4:5], |v25|, s17
	s_mov_b64 s[16:17], 0x4000
	s_nop 0
	v_cndmask_b32_e64 v25, v25, v26, s[4:5]
	v_cndmask_b32_e32 v26, 0, v178, vcc
	v_sub_f32_e32 v25, v25, v26
	v_add_f32_e32 v24, v24, v25
	v_mul_f32_e32 v145, 0xc1000000, v24
	v_lshlrev_b64 v[24:25], 12, v[42:43]
	v_lshl_add_u64 v[68:69], s[82:83], 0, v[24:25]
	v_mov_b64_e32 v[24:25], s[82:83]
	v_mad_i64_i32 v[70:71], s[4:5], v42, s33, v[24:25]
	s_mov_b64 s[4:5], 0
	v_lshl_add_u64 v[244:245], v[70:71], 0, v[30:31]
	v_lshl_add_u64 v[246:247], v[68:69], 0, v[30:31]
	v_add_co_u32_e32 v248, vcc, 0x6288000, v244
	s_nop 1
	v_addc_co_u32_e32 v249, vcc, 0, v245, vcc
	v_add_co_u32_e32 v250, vcc, 0x628c000, v244
	s_nop 1
	v_addc_co_u32_e32 v251, vcc, 0, v245, vcc
	v_add_co_u32_e32 v252, vcc, 0x6290000, v244
	s_nop 1
	v_addc_co_u32_e32 v253, vcc, 0, v245, vcc
	v_add_co_u32_e32 v194, vcc, 0x6294000, v244
	s_nop 1
	v_addc_co_u32_e32 v195, vcc, 0, v245, vcc
	v_add_co_u32_e32 v244, vcc, 0x16ea9000, v246
	s_nop 1
	v_addc_co_u32_e32 v245, vcc, 0, v247, vcc
	v_add_co_u32_e32 v246, vcc, 0x16eab000, v246
	s_nop 1
	v_addc_co_u32_e32 v247, vcc, 0, v247, vcc
	global_load_dwordx4 v[196:199], v[248:249], off
	global_load_dwordx4 v[200:203], v[244:245], off offset:-4096
	global_load_dwordx4 v[204:207], v[244:245], off offset:-2048
	global_load_dwordx4 v[208:211], v[250:251], off offset:512
	global_load_dwordx4 v[212:215], v[244:245], off
	global_load_dwordx4 v[216:219], v[244:245], off offset:2048
	global_load_dwordx4 v[220:223], v[252:253], off offset:1024
	global_load_dwordx4 v[224:227], v[246:247], off offset:-4096
	global_load_dwordx4 v[228:231], v[246:247], off offset:-2048
	global_load_dwordx4 v[232:235], v[194:195], off offset:1536
	global_load_dwordx4 v[236:239], v[246:247], off
	global_load_dwordx4 v[240:243], v[246:247], off offset:2048
	s_waitcnt vmcnt(0)
; __device__ __forceinline__ void unpack8(const u32x4 w, float (&f)[8]) { f[0] = bflo(w.x); f[1] = bfhi(w.x); f[2] = bflo(w.y); f[3] = bfhi(w.y); f[4] = bflo(w.z); f[5] = bfhi(w.z); f[6] = bflo(w.w); f[7] = bfhi(w.w); }
; __device__ __forceinline__ float sigmoidf_(float x) { return __builtin_amdgcn_rcpf(1.0f + __expf(-x)); }
; template <int FINAL>
; __device__ __forceinline__ void phase_lru(const Ctx& c, int p, int l) {
;     ...
;         for (int t4 = 0; t4 < g.n; t4 += 4) {
;           u32x4 rx[4], rr[4], ri[4];
; #pragma unroll
;           for (int u = 0; u < 4; ++u) { const size_t row = (size_t)(g.row0 + t4 + u); rx[u] = *(const u32x4*)(Z + row * ZW + C_LRU + ch); rr[u] = *(const u32x4*)(T + row * 2048 + ch); ri[u] = *(const u32x4*)(T + row * 2048 + 1024 + ch); }
; #pragma unroll
;           for (int u = 0; u < 4; ++u) {
;             const size_t row = (size_t)(g.row0 + t4 + u); float x[8], rp[8], ip[8];
;             unpack8(rx[u], x); unpack8(rr[u], rp); unpack8(ri[u], ip);
; #pragma unroll
;             for (int j = 0; j < 8; ++j) { const float la = c1[j] * sigmoidf_(rp[j] + ba[j]), a = __expf(la), bt = __builtin_amdgcn_sqrtf(fmaxf(1.0f - __expf(2.0f * la), 0.f)) * sigmoidf_(ip[j] + bx[j]) * x[j];
;                 B[j] = a * B[j] + bt; A[j] *= a; x[j] = B[j]; }
.LBB0_1143:
	v_lshl_add_u64 v[40:41], v[70:71], 0, v[30:31]
	v_add_co_u32_e32 v72, vcc, 0x6288000, v40
	s_nop 1
	v_addc_co_u32_e32 v73, vcc, 0, v41, vcc
	v_add_co_u32_e32 v74, vcc, 0x628c000, v40
	s_nop 1
	v_addc_co_u32_e32 v75, vcc, 0, v41, vcc
	v_add_co_u32_e32 v76, vcc, 0x6290000, v40
	s_nop 1
	v_addc_co_u32_e32 v77, vcc, 0, v41, vcc
	v_add_co_u32_e32 v78, vcc, 0x6294000, v40
	s_nop 1
	v_addc_co_u32_e32 v79, vcc, 0, v41, vcc
	s_add_i32 s14, s14, 4
	v_lshl_add_u64 v[68:69], v[68:69], 0, s[16:17]
	v_lshl_add_u64 v[70:71], v[70:71], 0, s[24:25]
	s_waitcnt vmcnt(4)
	v_mov_b64_e32 v[24:25], v[196:197]
	v_mov_b64_e32 v[26:27], v[198:199]
	v_mov_b64_e32 v[80:81], v[200:201]
	v_mov_b64_e32 v[82:83], v[202:203]
	v_mov_b64_e32 v[84:85], v[204:205]
	v_mov_b64_e32 v[86:87], v[206:207]
	v_mov_b64_e32 v[32:33], v[208:209]
	v_mov_b64_e32 v[34:35], v[210:211]
	v_mov_b64_e32 v[104:105], v[212:213]
	v_mov_b64_e32 v[106:107], v[214:215]
	v_mov_b64_e32 v[108:109], v[216:217]
	v_mov_b64_e32 v[110:111], v[218:219]
	v_mov_b64_e32 v[36:37], v[220:221]
	v_mov_b64_e32 v[38:39], v[222:223]
	v_mov_b64_e32 v[56:57], v[224:225]
	v_mov_b64_e32 v[58:59], v[226:227]
	v_mov_b64_e32 v[52:53], v[228:229]
	v_mov_b64_e32 v[54:55], v[230:231]
	v_mov_b64_e32 v[40:41], v[232:233]
	v_mov_b64_e32 v[42:43], v[234:235]
	v_mov_b64_e32 v[48:49], v[236:237]
	v_mov_b64_e32 v[50:51], v[238:239]
	v_mov_b64_e32 v[44:45], v[240:241]
	v_mov_b64_e32 v[46:47], v[242:243]
	v_lshl_add_u64 v[244:245], v[70:71], 0, v[30:31]
	v_lshl_add_u64 v[246:247], v[68:69], 0, v[30:31]
	v_add_co_u32_e32 v248, vcc, 0x6288000, v244
	s_nop 1
	v_addc_co_u32_e32 v249, vcc, 0, v245, vcc
	v_add_co_u32_e32 v250, vcc, 0x628c000, v244
	s_nop 1
	v_addc_co_u32_e32 v251, vcc, 0, v245, vcc
	v_add_co_u32_e32 v252, vcc, 0x6290000, v244
	s_nop 1
	v_addc_co_u32_e32 v253, vcc, 0, v245, vcc
	v_add_co_u32_e32 v194, vcc, 0x6294000, v244
	s_nop 1
	v_addc_co_u32_e32 v195, vcc, 0, v245, vcc
	v_add_co_u32_e32 v244, vcc, 0x16ea9000, v246
	s_nop 1
	v_addc_co_u32_e32 v245, vcc, 0, v247, vcc
	v_add_co_u32_e32 v246, vcc, 0x16eab000, v246
	s_nop 1
	v_addc_co_u32_e32 v247, vcc, 0, v247, vcc
	global_load_dwordx4 v[196:199], v[248:249], off
	global_load_dwordx4 v[200:203], v[244:245], off offset:-4096
	global_load_dwordx4 v[204:207], v[244:245], off offset:-2048
	global_load_dwordx4 v[208:211], v[250:251], off offset:512
	global_load_dwordx4 v[212:215], v[244:245], off
	global_load_dwordx4 v[216:219], v[244:245], off offset:2048
	global_load_dwordx4 v[220:223], v[252:253], off offset:1024
	global_load_dwordx4 v[224:227], v[246:247], off offset:-4096
	global_load_dwordx4 v[228:231], v[246:247], off offset:-2048
	global_load_dwordx4 v[232:235], v[194:195], off offset:1536
	global_load_dwordx4 v[236:239], v[246:247], off
	global_load_dwordx4 v[240:243], v[246:247], off offset:2048
	v_cmp_ge_u32_e32 vcc, s14, v129
	s_or_b64 s[4:5], vcc, s[4:5]
	v_lshlrev_b32_e32 v88, 16, v80
	v_lshlrev_b32_e32 v113, 16, v86
	v_and_b32_e32 v114, 0xffff0000, v86
	v_add_f32_e32 v86, v12, v88
	v_mul_f32_e32 v86, 0xbfb8aa3b, v86
	v_exp_f32_e32 v86, v86
	v_lshlrev_b32_e32 v115, 16, v87
	v_and_b32_e32 v116, 0xffff0000, v87
	v_and_b32_e32 v80, 0xffff0000, v80
	v_add_f32_e32 v86, 1.0, v86
	v_rcp_f32_e32 v86, v86
	v_add_f32_e32 v80, v13, v80
	v_mul_f32_e32 v80, 0xbfb8aa3b, v80
	v_exp_f32_e32 v80, v80
	v_mul_f32_e32 v86, v130, v86
	v_mul_f32_e32 v87, 0x3fb8aa3b, v86
	v_add_f32_e32 v86, v86, v86
	v_mul_f32_e32 v86, 0x3fb8aa3b, v86
	v_exp_f32_e32 v86, v86
	v_lshlrev_b32_e32 v91, 16, v84
	v_add_f32_e32 v80, 1.0, v80
	v_rcp_f32_e32 v80, v80
	v_sub_f32_e32 v86, 1.0, v86
	v_max_f32_e32 v86, 0, v86
	v_sqrt_f32_e32 v100, v86
	v_add_f32_e32 v86, v20, v91
	v_mul_f32_e32 v86, 0xbfb8aa3b, v86
	v_exp_f32_e32 v86, v86
	v_mul_f32_e32 v80, v131, v80
	v_and_b32_e32 v84, 0xffff0000, v84
	v_lshlrev_b32_e32 v89, 16, v81
	v_add_f32_e32 v86, 1.0, v86
	v_rcp_f32_e32 v102, v86
	v_mul_f32_e32 v86, 0x3fb8aa3b, v80
	v_add_f32_e32 v80, v80, v80
	v_mul_f32_e32 v80, 0x3fb8aa3b, v80
	v_exp_f32_e32 v80, v80
	v_lshlrev_b32_e32 v93, 16, v85
	v_and_b32_e32 v81, 0xffff0000, v81
	v_and_b32_e32 v85, 0xffff0000, v85
	v_sub_f32_e32 v80, 1.0, v80
	v_max_f32_e32 v80, 0, v80
	v_sqrt_f32_e32 v101, v80
	v_add_f32_e32 v80, v21, v84
	v_mul_f32_e32 v80, 0xbfb8aa3b, v80
	v_exp_f32_e32 v80, v80
	v_lshlrev_b32_e32 v90, 16, v82
	v_and_b32_e32 v82, 0xffff0000, v82
	v_exp_f32_e32 v99, v86
	v_add_f32_e32 v80, 1.0, v80
	v_rcp_f32_e32 v103, v80
	v_add_f32_e32 v80, v14, v89
	v_mul_f32_e32 v80, 0xbfb8aa3b, v80
	v_exp_f32_e32 v80, v80
	v_lshlrev_b32_e32 v112, 16, v83
	v_lshlrev_b32_e32 v137, 16, v110
	v_and_b32_e32 v138, 0xffff0000, v110
	v_add_f32_e32 v80, 1.0, v80
	v_rcp_f32_e32 v80, v80
	v_exp_f32_e32 v98, v87
	v_lshlrev_b32_e32 v139, 16, v111
	v_and_b32_e32 v146, 0xffff0000, v111
	v_mul_f32_e32 v80, v132, v80
	v_mul_f32_e32 v84, 0x3fb8aa3b, v80
	v_add_f32_e32 v80, v80, v80
	v_mul_f32_e32 v80, 0x3fb8aa3b, v80
	v_exp_f32_e32 v80, v80
	v_lshlrev_b32_e32 v117, 16, v109
	v_and_b32_e32 v109, 0xffff0000, v109
	v_lshlrev_b32_e32 v136, 16, v107
	v_sub_f32_e32 v80, 1.0, v80
	v_max_f32_e32 v80, 0, v80
	v_sqrt_f32_e32 v94, v80
	v_add_f32_e32 v80, v22, v93
	v_mul_f32_e32 v80, 0xbfb8aa3b, v80
	v_exp_f32_e32 v80, v80
	v_lshlrev_b32_e32 v160, 16, v55
	v_and_b32_e32 v161, 0xffff0000, v55
	v_lshlrev_b32_e32 v154, 16, v58
	v_add_f32_e32 v80, 1.0, v80
	v_rcp_f32_e32 v96, v80
	v_add_f32_e32 v80, v15, v81
	v_mul_f32_e32 v80, 0xbfb8aa3b, v80
	v_exp_f32_e32 v80, v80
	v_and_b32_e32 v155, 0xffff0000, v58
	v_lshlrev_b32_e32 v58, 16, v52
	v_and_b32_e32 v52, 0xffff0000, v52
	v_add_f32_e32 v80, 1.0, v80
	v_rcp_f32_e32 v80, v80
	v_add_f32_e32 v52, v21, v52
; __device__ __forceinline__ void unpack8(const u32x4 w, float (&f)[8]) { f[0] = bflo(w.x); f[1] = bfhi(w.x); f[2] = bflo(w.y); f[3] = bfhi(w.y); f[4] = bflo(w.z); f[5] = bfhi(w.z); f[6] = bflo(w.w); f[7] = bfhi(w.w); }
; __device__ __forceinline__ u32x4 pack8(const float (&f)[8]) { u32x4 w; w.x = pk2(f[0], f[1]); w.y = pk2(f[2], f[3]); w.z = pk2(f[4], f[5]); w.w = pk2(f[6], f[7]); return w; }
; __device__ __forceinline__ float sigmoidf_(float x) { return __builtin_amdgcn_rcpf(1.0f + __expf(-x)); }
; template <int FINAL>
; __device__ __forceinline__ void phase_lru(const Ctx& c, int p, int l) {
;     ...
;           for (int u = 0; u < 4; ++u) {
;             const size_t row = (size_t)(g.row0 + t4 + u); float x[8], rp[8], ip[8];
;             unpack8(rx[u], x); unpack8(rr[u], rp); unpack8(ri[u], ip);
; #pragma unroll
;             for (int j = 0; j < 8; ++j) { const float la = c1[j] * sigmoidf_(rp[j] + ba[j]), a = __expf(la), bt = __builtin_amdgcn_sqrtf(fmaxf(1.0f - __expf(2.0f * la), 0.f)) * sigmoidf_(ip[j] + bx[j]) * x[j];
;                 B[j] = a * B[j] + bt; A[j] *= a; x[j] = B[j]; }
;             if (FINAL) *(u32x4*)(Z + row * ZW + C_LRU + ch) = pack8(x);
	v_mul_f32_e32 v52, 0xbfb8aa3b, v52
	v_exp_f32_e32 v52, v52
	v_mul_f32_e32 v80, v133, v80
	v_mul_f32_e32 v81, 0x3fb8aa3b, v80
	v_add_f32_e32 v80, v80, v80
	v_mul_f32_e32 v80, 0x3fb8aa3b, v80
	v_exp_f32_e32 v80, v80
	v_exp_f32_e32 v93, v81
	v_lshlrev_b32_e32 v148, 16, v57
	v_add_f32_e32 v52, 1.0, v52
	v_sub_f32_e32 v80, 1.0, v80
	v_max_f32_e32 v80, 0, v80
	v_sqrt_f32_e32 v95, v80
	v_add_f32_e32 v80, v23, v85
	v_mul_f32_e32 v80, 0xbfb8aa3b, v80
	v_exp_f32_e32 v80, v80
	v_rcp_f32_e32 v147, v52
	v_add_f32_e32 v52, v14, v148
	v_mul_f32_e32 v52, 0xbfb8aa3b, v52
	v_add_f32_e32 v80, 1.0, v80
	v_rcp_f32_e32 v97, v80
	v_add_f32_e32 v80, v8, v90
	v_mul_f32_e32 v80, 0xbfb8aa3b, v80
	v_exp_f32_e32 v80, v80
	v_exp_f32_e32 v52, v52
	v_lshlrev_b32_e32 v158, 16, v59
	v_and_b32_e32 v159, 0xffff0000, v59
	v_add_f32_e32 v80, 1.0, v80
	v_rcp_f32_e32 v80, v80
	v_add_f32_e32 v52, 1.0, v52
	v_rcp_f32_e32 v52, v52
	v_lshlrev_b32_e32 v59, 16, v53
	v_mul_f32_e32 v80, v134, v80
	v_mul_f32_e32 v81, 0x3fb8aa3b, v80
	v_add_f32_e32 v80, v80, v80
	v_mul_f32_e32 v80, 0x3fb8aa3b, v80
	v_exp_f32_e32 v80, v80
	v_exp_f32_e32 v86, v81
	v_mul_f32_e32 v52, v132, v52
	v_and_b32_e32 v57, 0xffff0000, v57
	v_sub_f32_e32 v80, 1.0, v80
	v_max_f32_e32 v80, 0, v80
	v_sqrt_f32_e32 v88, v80
	v_add_f32_e32 v80, v16, v113
	v_mul_f32_e32 v80, 0xbfb8aa3b, v80
	v_exp_f32_e32 v80, v80
	v_lshlrev_b32_e32 v113, 16, v105
	v_and_b32_e32 v105, 0xffff0000, v105
	v_and_b32_e32 v53, 0xffff0000, v53
	v_add_f32_e32 v80, 1.0, v80
	v_rcp_f32_e32 v90, v80
	v_add_f32_e32 v80, v9, v82
	v_mul_f32_e32 v80, 0xbfb8aa3b, v80
	v_exp_f32_e32 v80, v80
	v_lshlrev_b32_e32 v156, 16, v54
	v_and_b32_e32 v54, 0xffff0000, v54
	v_lshlrev_b32_e32 v188, 16, v45
	v_add_f32_e32 v80, 1.0, v80
	v_rcp_f32_e32 v80, v80
	v_and_b32_e32 v189, 0xffff0000, v45
	v_lshlrev_b32_e32 v190, 16, v46
	v_and_b32_e32 v191, 0xffff0000, v46
	v_mul_f32_e32 v80, v135, v80
	v_mul_f32_e32 v81, 0x3fb8aa3b, v80
	v_add_f32_e32 v80, v80, v80
	v_mul_f32_e32 v80, 0x3fb8aa3b, v80
	v_exp_f32_e32 v80, v80
	v_exp_f32_e32 v87, v81
	v_lshlrev_b32_e32 v184, 16, v50
	v_and_b32_e32 v185, 0xffff0000, v50
	v_sub_f32_e32 v80, 1.0, v80
	v_max_f32_e32 v80, 0, v80
	v_sqrt_f32_e32 v89, v80
	v_add_f32_e32 v80, v17, v114
	v_mul_f32_e32 v80, 0xbfb8aa3b, v80
	v_exp_f32_e32 v80, v80
	v_lshlrev_b32_e32 v114, 16, v106
	v_and_b32_e32 v106, 0xffff0000, v106
	v_lshlrev_b32_e32 v186, 16, v51
	v_add_f32_e32 v80, 1.0, v80
	v_rcp_f32_e32 v91, v80
	v_add_f32_e32 v80, v10, v112
	v_lshlrev_b32_e32 v112, 16, v104
	v_mul_f32_e32 v80, 0xbfb8aa3b, v80
	v_add_f32_e32 v110, v12, v112
	v_exp_f32_e32 v80, v80
	v_mul_f32_e32 v110, 0xbfb8aa3b, v110
	v_exp_f32_e32 v110, v110
	v_and_b32_e32 v104, 0xffff0000, v104
	v_add_f32_e32 v80, 1.0, v80
	v_rcp_f32_e32 v80, v80
	v_add_f32_e32 v110, 1.0, v110
	v_rcp_f32_e32 v110, v110
	v_add_f32_e32 v104, v13, v104
	v_mul_f32_e32 v81, v144, v80
	v_mul_f32_e32 v80, 0x3fb8aa3b, v81
	v_add_f32_e32 v81, v81, v81
	v_mul_f32_e32 v110, v130, v110
	v_mul_f32_e32 v81, 0x3fb8aa3b, v81
	v_mul_f32_e32 v111, 0x3fb8aa3b, v110
	v_add_f32_e32 v110, v110, v110
	v_exp_f32_e32 v81, v81
	v_mul_f32_e32 v110, 0x3fb8aa3b, v110
	v_exp_f32_e32 v110, v110
	v_mul_f32_e32 v104, 0xbfb8aa3b, v104
	v_sub_f32_e32 v81, 1.0, v81
	v_exp_f32_e32 v104, v104
	v_max_f32_e32 v81, 0, v81
	v_sub_f32_e32 v110, 1.0, v110
	v_sqrt_f32_e32 v82, v81
	v_add_f32_e32 v81, v18, v115
	v_lshlrev_b32_e32 v115, 16, v108
	v_max_f32_e32 v110, 0, v110
	v_sqrt_f32_e32 v124, v110
	v_add_f32_e32 v110, v20, v115
	v_mul_f32_e32 v110, 0xbfb8aa3b, v110
	v_add_f32_e32 v104, 1.0, v104
	v_exp_f32_e32 v110, v110
	v_rcp_f32_e32 v104, v104
	v_and_b32_e32 v108, 0xffff0000, v108
	v_exp_f32_e32 v122, v111
	v_add_f32_e32 v110, 1.0, v110
	v_mul_f32_e32 v104, v131, v104
	v_rcp_f32_e32 v126, v110
	v_mul_f32_e32 v110, 0x3fb8aa3b, v104
	v_add_f32_e32 v104, v104, v104
	v_mul_f32_e32 v104, 0x3fb8aa3b, v104
	v_exp_f32_e32 v104, v104
	v_exp_f32_e32 v123, v110
	v_and_b32_e32 v187, 0xffff0000, v51
	v_lshlrev_b32_e32 v50, 16, v24
	v_sub_f32_e32 v104, 1.0, v104
	v_max_f32_e32 v104, 0, v104
	v_sqrt_f32_e32 v125, v104
	v_add_f32_e32 v104, v21, v108
	v_mul_f32_e32 v104, 0xbfb8aa3b, v104
	v_exp_f32_e32 v104, v104
	v_and_b32_e32 v51, 0xffff0000, v24
	v_pk_mul_f32 v[100:101], v[102:103], v[100:101]
	v_lshlrev_b32_e32 v192, 16, v47
	v_add_f32_e32 v104, 1.0, v104
	v_rcp_f32_e32 v127, v104
	v_add_f32_e32 v104, v14, v113
	v_mul_f32_e32 v104, 0xbfb8aa3b, v104
	v_exp_f32_e32 v104, v104
	v_pk_mul_f32 v[50:51], v[100:101], v[50:51]
	v_and_b32_e32 v193, 0xffff0000, v47
	v_pk_fma_f32 v[0:1], v[0:1], v[98:99], v[50:51]
	v_add_f32_e32 v104, 1.0, v104
	v_rcp_f32_e32 v104, v104
	v_lshlrev_b32_e32 v50, 16, v32
	v_and_b32_e32 v51, 0xffff0000, v32
	v_pk_mul_f32 v[98:99], v[126:127], v[124:125]
	v_mul_f32_e32 v104, v132, v104
	v_mul_f32_e32 v108, 0x3fb8aa3b, v104
	v_add_f32_e32 v104, v104, v104
	v_mul_f32_e32 v104, 0x3fb8aa3b, v104
	v_exp_f32_e32 v104, v104
	v_pk_mul_f32 v[50:51], v[98:99], v[50:51]
	v_cvt_pk_bf16_f32 v24, v0, v1
	v_pk_fma_f32 v[0:1], v[122:123], v[0:1], v[50:51]
	v_sub_f32_e32 v104, 1.0, v104
	v_max_f32_e32 v104, 0, v104
	v_sqrt_f32_e32 v118, v104
	v_add_f32_e32 v104, v22, v117
	v_mul_f32_e32 v104, 0xbfb8aa3b, v104
	v_exp_f32_e32 v104, v104
	v_lshlrev_b32_e32 v50, 16, v36
	v_and_b32_e32 v51, 0xffff0000, v36
	v_cvt_pk_bf16_f32 v32, v0, v1
	v_add_f32_e32 v104, 1.0, v104
	v_rcp_f32_e32 v120, v104
	v_add_f32_e32 v104, v15, v105
	v_mul_f32_e32 v104, 0xbfb8aa3b, v104
	v_exp_f32_e32 v104, v104
	v_exp_f32_e32 v92, v84
	v_add_f32_e32 v85, v19, v116
	v_exp_f32_e32 v116, v108
	v_add_f32_e32 v104, 1.0, v104
	v_rcp_f32_e32 v104, v104
	v_pk_mul_f32 v[94:95], v[96:97], v[94:95]
; __device__ __forceinline__ void unpack8(const u32x4 w, float (&f)[8]) { f[0] = bflo(w.x); f[1] = bfhi(w.x); f[2] = bflo(w.y); f[3] = bfhi(w.y); f[4] = bflo(w.z); f[5] = bfhi(w.z); f[6] = bflo(w.w); f[7] = bfhi(w.w); }
; __device__ __forceinline__ float sigmoidf_(float x) { return __builtin_amdgcn_rcpf(1.0f + __expf(-x)); }
; template <int FINAL>
; __device__ __forceinline__ void phase_lru(const Ctx& c, int p, int l) {
;     ...
;           for (int u = 0; u < 4; ++u) {
;             const size_t row = (size_t)(g.row0 + t4 + u); float x[8], rp[8], ip[8];
;             unpack8(rx[u], x); unpack8(rr[u], rp); unpack8(ri[u], ip);
; #pragma unroll
;             for (int j = 0; j < 8; ++j) { const float la = c1[j] * sigmoidf_(rp[j] + ba[j]), a = __expf(la), bt = __builtin_amdgcn_sqrtf(fmaxf(1.0f - __expf(2.0f * la), 0.f)) * sigmoidf_(ip[j] + bx[j]) * x[j];
;                 B[j] = a * B[j] + bt; A[j] *= a; x[j] = B[j]; }
	v_mul_f32_e32 v81, 0xbfb8aa3b, v81
	v_exp_f32_e32 v81, v81
	v_mul_f32_e32 v104, v133, v104
	v_mul_f32_e32 v105, 0x3fb8aa3b, v104
	v_add_f32_e32 v104, v104, v104
	v_mul_f32_e32 v104, 0x3fb8aa3b, v104
	v_exp_f32_e32 v104, v104
	v_exp_f32_e32 v117, v105
	v_and_b32_e32 v83, 0xffff0000, v83
	v_add_f32_e32 v81, 1.0, v81
	v_sub_f32_e32 v104, 1.0, v104
	v_max_f32_e32 v104, 0, v104
	v_sqrt_f32_e32 v119, v104
	v_add_f32_e32 v104, v23, v109
	v_mul_f32_e32 v104, 0xbfb8aa3b, v104
	v_exp_f32_e32 v104, v104
	v_add_f32_e32 v109, v19, v146
	v_rcp_f32_e32 v84, v81
	v_add_f32_e32 v81, v11, v83
	v_add_f32_e32 v104, 1.0, v104
	v_rcp_f32_e32 v121, v104
	v_add_f32_e32 v104, v8, v114
	v_mul_f32_e32 v104, 0xbfb8aa3b, v104
	v_exp_f32_e32 v104, v104
	v_mul_f32_e32 v81, 0xbfb8aa3b, v81
	v_and_b32_e32 v107, 0xffff0000, v107
	v_exp_f32_e32 v81, v81
	v_add_f32_e32 v104, 1.0, v104
	v_rcp_f32_e32 v104, v104
	v_mul_f32_e32 v85, 0xbfb8aa3b, v85
	v_add_f32_e32 v81, 1.0, v81
	v_rcp_f32_e32 v81, v81
	v_mul_f32_e32 v104, v134, v104
	v_mul_f32_e32 v105, 0x3fb8aa3b, v104
	v_add_f32_e32 v104, v104, v104
	v_mul_f32_e32 v104, 0x3fb8aa3b, v104
	v_exp_f32_e32 v104, v104
	v_exp_f32_e32 v110, v105
	v_mul_f32_e32 v83, v145, v81
	v_mul_f32_e32 v81, 0x3fb8aa3b, v83
	v_sub_f32_e32 v104, 1.0, v104
	v_max_f32_e32 v104, 0, v104
	v_sqrt_f32_e32 v112, v104
	v_add_f32_e32 v104, v16, v137
	v_mul_f32_e32 v104, 0xbfb8aa3b, v104
	v_exp_f32_e32 v104, v104
	v_add_f32_e32 v83, v83, v83
	v_mul_f32_e32 v83, 0x3fb8aa3b, v83
	v_exp_f32_e32 v83, v83
	v_add_f32_e32 v104, 1.0, v104
	v_rcp_f32_e32 v114, v104
	v_add_f32_e32 v104, v9, v106
	v_mul_f32_e32 v104, 0xbfb8aa3b, v104
	v_exp_f32_e32 v104, v104
	v_exp_f32_e32 v85, v85
	v_mul_f32_e32 v109, 0xbfb8aa3b, v109
	v_exp_f32_e32 v109, v109
	v_add_f32_e32 v104, 1.0, v104
	v_rcp_f32_e32 v104, v104
	v_sub_f32_e32 v83, 1.0, v83
	v_max_f32_e32 v83, 0, v83
	v_add_f32_e32 v85, 1.0, v85
	v_mul_f32_e32 v104, v135, v104
	v_mul_f32_e32 v105, 0x3fb8aa3b, v104
	v_add_f32_e32 v104, v104, v104
	v_mul_f32_e32 v104, 0x3fb8aa3b, v104
	v_exp_f32_e32 v104, v104
	v_exp_f32_e32 v111, v105
	v_sqrt_f32_e32 v83, v83
	v_rcp_f32_e32 v85, v85
	v_sub_f32_e32 v104, 1.0, v104
	v_max_f32_e32 v104, 0, v104
	v_sqrt_f32_e32 v113, v104
	v_add_f32_e32 v104, v17, v138
	v_mul_f32_e32 v104, 0xbfb8aa3b, v104
	v_exp_f32_e32 v104, v104
	v_add_f32_e32 v109, 1.0, v109
	v_exp_f32_e32 v80, v80
	v_exp_f32_e32 v81, v81
	v_add_f32_e32 v104, 1.0, v104
	v_rcp_f32_e32 v115, v104
	v_add_f32_e32 v104, v10, v136
	v_lshlrev_b32_e32 v136, 16, v56
	v_add_f32_e32 v55, v12, v136
	v_mul_f32_e32 v55, 0xbfb8aa3b, v55
	v_exp_f32_e32 v55, v55
	v_and_b32_e32 v56, 0xffff0000, v56
	v_mul_f32_e32 v104, 0xbfb8aa3b, v104
	v_exp_f32_e32 v104, v104
	v_add_f32_e32 v55, 1.0, v55
	v_rcp_f32_e32 v55, v55
	v_rcp_f32_e32 v109, v109
	v_add_f32_e32 v104, 1.0, v104
	v_rcp_f32_e32 v104, v104
	v_mul_f32_e32 v55, v130, v55
	v_mul_f32_e32 v136, 0x3fb8aa3b, v55
	v_add_f32_e32 v55, v55, v55
	v_mul_f32_e32 v55, 0x3fb8aa3b, v55
	v_exp_f32_e32 v55, v55
	v_mul_f32_e32 v105, v144, v104
	v_mul_f32_e32 v104, 0x3fb8aa3b, v105
	v_add_f32_e32 v105, v105, v105
	v_sub_f32_e32 v55, 1.0, v55
	v_max_f32_e32 v55, 0, v55
	v_sqrt_f32_e32 v138, v55
	v_add_f32_e32 v55, v20, v58
	v_mul_f32_e32 v55, 0xbfb8aa3b, v55
	v_exp_f32_e32 v55, v55
	v_mul_f32_e32 v105, 0x3fb8aa3b, v105
	v_exp_f32_e32 v105, v105
	v_exp_f32_e32 v136, v136
	v_add_f32_e32 v55, 1.0, v55
	v_rcp_f32_e32 v146, v55
	v_add_f32_e32 v55, v13, v56
	v_mul_f32_e32 v55, 0xbfb8aa3b, v55
	v_exp_f32_e32 v55, v55
	v_sub_f32_e32 v105, 1.0, v105
	v_max_f32_e32 v105, 0, v105
	v_sqrt_f32_e32 v106, v105
	v_add_f32_e32 v55, 1.0, v55
	v_rcp_f32_e32 v55, v55
	v_add_f32_e32 v105, v18, v139
	v_mul_f32_e32 v105, 0xbfb8aa3b, v105
	v_exp_f32_e32 v105, v105
	v_mul_f32_e32 v55, v131, v55
	v_mul_f32_e32 v56, 0x3fb8aa3b, v55
	v_add_f32_e32 v55, v55, v55
	v_mul_f32_e32 v55, 0x3fb8aa3b, v55
	v_exp_f32_e32 v55, v55
	v_exp_f32_e32 v137, v56
	v_add_f32_e32 v105, 1.0, v105
	v_rcp_f32_e32 v108, v105
	v_sub_f32_e32 v55, 1.0, v55
	v_max_f32_e32 v55, 0, v55
	v_sqrt_f32_e32 v139, v55
	v_mul_f32_e32 v55, 0x3fb8aa3b, v52
	v_add_f32_e32 v52, v52, v52
	v_mul_f32_e32 v52, 0x3fb8aa3b, v52
	v_exp_f32_e32 v52, v52
	v_exp_f32_e32 v148, v55
	v_pk_mul_f32 v[98:99], v[146:147], v[138:139]
	v_add_f32_e32 v105, v11, v107
	v_sub_f32_e32 v52, 1.0, v52
	v_max_f32_e32 v52, 0, v52
	v_sqrt_f32_e32 v150, v52
	v_add_f32_e32 v52, v22, v59
	v_mul_f32_e32 v52, 0xbfb8aa3b, v52
	v_exp_f32_e32 v52, v52
	v_pk_mul_f32 v[50:51], v[98:99], v[50:51]
	v_mul_f32_e32 v105, 0xbfb8aa3b, v105
	v_pk_fma_f32 v[0:1], v[136:137], v[0:1], v[50:51]
	v_add_f32_e32 v52, 1.0, v52
	v_rcp_f32_e32 v152, v52
	v_add_f32_e32 v52, v15, v57
	v_mul_f32_e32 v52, 0xbfb8aa3b, v52
	v_exp_f32_e32 v52, v52
	v_add_f32_e32 v57, v19, v161
	v_and_b32_e32 v161, 0xffff0000, v49
	v_lshlrev_b32_e32 v50, 16, v40
	v_add_f32_e32 v52, 1.0, v52
	v_rcp_f32_e32 v52, v52
	v_and_b32_e32 v51, 0xffff0000, v40
	v_cvt_pk_bf16_f32 v36, v0, v1
	v_exp_f32_e32 v105, v105
	v_mul_f32_e32 v52, v133, v52
	v_mul_f32_e32 v55, 0x3fb8aa3b, v52
	v_add_f32_e32 v52, v52, v52
	v_mul_f32_e32 v52, 0x3fb8aa3b, v52
	v_exp_f32_e32 v52, v52
	v_exp_f32_e32 v149, v55
	v_add_f32_e32 v105, 1.0, v105
	v_rcp_f32_e32 v105, v105
	v_sub_f32_e32 v52, 1.0, v52
	v_max_f32_e32 v52, 0, v52
	v_sqrt_f32_e32 v151, v52
	v_add_f32_e32 v52, v23, v53
	v_mul_f32_e32 v52, 0xbfb8aa3b, v52
	v_exp_f32_e32 v52, v52
	v_mul_f32_e32 v107, v145, v105
	v_mul_f32_e32 v105, 0x3fb8aa3b, v107
	v_add_f32_e32 v107, v107, v107
	v_add_f32_e32 v52, 1.0, v52
	v_rcp_f32_e32 v153, v52
	v_add_f32_e32 v52, v8, v154
	v_mul_f32_e32 v52, 0xbfb8aa3b, v52
	v_exp_f32_e32 v52, v52
; __device__ __forceinline__ void unpack8(const u32x4 w, float (&f)[8]) { f[0] = bflo(w.x); f[1] = bfhi(w.x); f[2] = bflo(w.y); f[3] = bfhi(w.y); f[4] = bflo(w.z); f[5] = bfhi(w.z); f[6] = bflo(w.w); f[7] = bfhi(w.w); }
; __device__ __forceinline__ u32x4 pack8(const float (&f)[8]) { u32x4 w; w.x = pk2(f[0], f[1]); w.y = pk2(f[2], f[3]); w.z = pk2(f[4], f[5]); w.w = pk2(f[6], f[7]); return w; }
; __device__ __forceinline__ float sigmoidf_(float x) { return __builtin_amdgcn_rcpf(1.0f + __expf(-x)); }
; template <int FINAL>
; __device__ __forceinline__ void phase_lru(const Ctx& c, int p, int l) {
;     ...
;           for (int u = 0; u < 4; ++u) {
;             const size_t row = (size_t)(g.row0 + t4 + u); float x[8], rp[8], ip[8];
;             unpack8(rx[u], x); unpack8(rr[u], rp); unpack8(ri[u], ip);
; #pragma unroll
;             for (int j = 0; j < 8; ++j) { const float la = c1[j] * sigmoidf_(rp[j] + ba[j]), a = __expf(la), bt = __builtin_amdgcn_sqrtf(fmaxf(1.0f - __expf(2.0f * la), 0.f)) * sigmoidf_(ip[j] + bx[j]) * x[j];
;                 B[j] = a * B[j] + bt; A[j] *= a; x[j] = B[j]; }
;             if (FINAL) *(u32x4*)(Z + row * ZW + C_LRU + ch) = pack8(x);
	v_mul_f32_e32 v107, 0x3fb8aa3b, v107
	v_exp_f32_e32 v107, v107
	v_mul_f32_e32 v57, 0xbfb8aa3b, v57
	v_add_f32_e32 v52, 1.0, v52
	v_rcp_f32_e32 v52, v52
	v_exp_f32_e32 v57, v57
	v_sub_f32_e32 v107, 1.0, v107
	v_max_f32_e32 v107, 0, v107
	v_mul_f32_e32 v52, v134, v52
	v_mul_f32_e32 v53, 0x3fb8aa3b, v52
	v_add_f32_e32 v52, v52, v52
	v_mul_f32_e32 v52, 0x3fb8aa3b, v52
	v_exp_f32_e32 v52, v52
	v_exp_f32_e32 v58, v53
	v_sqrt_f32_e32 v107, v107
	v_add_f32_e32 v57, 1.0, v57
	v_sub_f32_e32 v52, 1.0, v52
	v_max_f32_e32 v52, 0, v52
	v_sqrt_f32_e32 v154, v52
	v_add_f32_e32 v52, v16, v156
	v_mul_f32_e32 v52, 0xbfb8aa3b, v52
	v_exp_f32_e32 v52, v52
	v_exp_f32_e32 v104, v104
	v_exp_f32_e32 v105, v105
	v_rcp_f32_e32 v57, v57
	v_add_f32_e32 v52, 1.0, v52
	v_rcp_f32_e32 v156, v52
	v_add_f32_e32 v52, v9, v155
	v_mul_f32_e32 v52, 0xbfb8aa3b, v52
	v_exp_f32_e32 v52, v52
	s_nop 0
	v_add_f32_e32 v52, 1.0, v52
	v_rcp_f32_e32 v52, v52
	s_nop 0
	v_mul_f32_e32 v52, v135, v52
	v_mul_f32_e32 v53, 0x3fb8aa3b, v52
	v_add_f32_e32 v52, v52, v52
	v_mul_f32_e32 v52, 0x3fb8aa3b, v52
	v_exp_f32_e32 v52, v52
	v_exp_f32_e32 v59, v53
	v_sub_f32_e32 v52, 1.0, v52
	v_max_f32_e32 v52, 0, v52
	v_sqrt_f32_e32 v155, v52
	v_add_f32_e32 v52, v17, v54
	v_mul_f32_e32 v52, 0xbfb8aa3b, v52
	v_exp_f32_e32 v52, v52
	s_nop 0
	v_add_f32_e32 v52, 1.0, v52
	v_rcp_f32_e32 v157, v52
	v_add_f32_e32 v52, v10, v158
	v_mul_f32_e32 v52, 0xbfb8aa3b, v52
	v_exp_f32_e32 v52, v52
	v_lshlrev_b32_e32 v158, 16, v48
	v_add_f32_e32 v52, 1.0, v52
	v_rcp_f32_e32 v52, v52
	s_nop 0
	v_mul_f32_e32 v53, v144, v52
	v_mul_f32_e32 v52, 0x3fb8aa3b, v53
	v_add_f32_e32 v53, v53, v53
	v_mul_f32_e32 v53, 0x3fb8aa3b, v53
	v_exp_f32_e32 v53, v53
	v_exp_f32_e32 v52, v52
	v_sub_f32_e32 v53, 1.0, v53
	v_max_f32_e32 v53, 0, v53
	v_sqrt_f32_e32 v54, v53
	v_add_f32_e32 v53, v18, v160
	v_mul_f32_e32 v53, 0xbfb8aa3b, v53
	v_exp_f32_e32 v53, v53
	v_lshlrev_b32_e32 v160, 16, v49
	v_and_b32_e32 v49, 0xffff0000, v44
	v_add_f32_e32 v49, v21, v49
	v_add_f32_e32 v53, 1.0, v53
	v_rcp_f32_e32 v56, v53
	v_add_f32_e32 v53, v11, v159
	v_and_b32_e32 v159, 0xffff0000, v48
	v_lshlrev_b32_e32 v48, 16, v44
	v_add_f32_e32 v44, v12, v158
	v_mul_f32_e32 v44, 0xbfb8aa3b, v44
	v_exp_f32_e32 v44, v44
	v_mul_f32_e32 v49, 0xbfb8aa3b, v49
	v_add_f32_e32 v40, v14, v160
	v_exp_f32_e32 v49, v49
	v_add_f32_e32 v44, 1.0, v44
	v_rcp_f32_e32 v44, v44
	v_mul_f32_e32 v40, 0xbfb8aa3b, v40
	v_exp_f32_e32 v40, v40
	v_add_f32_e32 v49, 1.0, v49
	v_mul_f32_e32 v45, v130, v44
	v_mul_f32_e32 v44, 0x3fb8aa3b, v45
	v_add_f32_e32 v45, v45, v45
	v_mul_f32_e32 v45, 0x3fb8aa3b, v45
	v_exp_f32_e32 v45, v45
	v_rcp_f32_e32 v49, v49
	v_add_f32_e32 v40, 1.0, v40
	v_rcp_f32_e32 v40, v40
	v_sub_f32_e32 v45, 1.0, v45
	v_max_f32_e32 v45, 0, v45
	v_sqrt_f32_e32 v46, v45
	v_add_f32_e32 v45, v20, v48
	v_mul_f32_e32 v45, 0xbfb8aa3b, v45
	v_exp_f32_e32 v45, v45
	v_exp_f32_e32 v44, v44
	v_mul_f32_e32 v40, v132, v40
	v_mul_f32_e32 v53, 0xbfb8aa3b, v53
	v_add_f32_e32 v45, 1.0, v45
	v_rcp_f32_e32 v48, v45
	v_add_f32_e32 v45, v13, v159
	v_mul_f32_e32 v45, 0xbfb8aa3b, v45
	v_exp_f32_e32 v45, v45
	v_exp_f32_e32 v53, v53
	v_add_f32_e32 v45, 1.0, v45
	v_rcp_f32_e32 v45, v45
	v_add_f32_e32 v53, 1.0, v53
	v_rcp_f32_e32 v53, v53
	v_mul_f32_e32 v47, v131, v45
	v_mul_f32_e32 v45, 0x3fb8aa3b, v47
	v_add_f32_e32 v47, v47, v47
	v_mul_f32_e32 v47, 0x3fb8aa3b, v47
	v_exp_f32_e32 v47, v47
	v_exp_f32_e32 v45, v45
	v_mul_f32_e32 v55, v145, v53
	v_mul_f32_e32 v53, 0x3fb8aa3b, v55
	v_sub_f32_e32 v47, 1.0, v47
	v_max_f32_e32 v47, 0, v47
	v_sqrt_f32_e32 v47, v47
	v_add_f32_e32 v55, v55, v55
	v_mul_f32_e32 v55, 0x3fb8aa3b, v55
	v_exp_f32_e32 v55, v55
	v_pk_mul_f32 v[46:47], v[48:49], v[46:47]
	v_exp_f32_e32 v53, v53
	v_pk_mul_f32 v[46:47], v[46:47], v[50:51]
	v_lshlrev_b32_e32 v50, 16, v25
	v_pk_fma_f32 v[0:1], v[44:45], v[0:1], v[46:47]
	v_mul_f32_e32 v44, 0x3fb8aa3b, v40
	v_add_f32_e32 v40, v40, v40
	v_mul_f32_e32 v40, 0x3fb8aa3b, v40
	v_exp_f32_e32 v40, v40
	v_and_b32_e32 v51, 0xffff0000, v25
	v_pk_mul_f32 v[50:51], v[94:95], v[50:51]
	v_exp_f32_e32 v44, v44
	v_sub_f32_e32 v40, 1.0, v40
	v_max_f32_e32 v40, 0, v40
	v_sqrt_f32_e32 v46, v40
	v_add_f32_e32 v40, v22, v188
	v_mul_f32_e32 v40, 0xbfb8aa3b, v40
	v_exp_f32_e32 v40, v40
	v_pk_fma_f32 v[2:3], v[2:3], v[92:93], v[50:51]
	v_lshlrev_b32_e32 v50, 16, v33
	v_and_b32_e32 v51, 0xffff0000, v33
	v_add_f32_e32 v40, 1.0, v40
	v_rcp_f32_e32 v48, v40
	v_add_f32_e32 v40, v15, v161
	v_mul_f32_e32 v40, 0xbfb8aa3b, v40
	v_exp_f32_e32 v40, v40
	v_pk_mul_f32 v[92:93], v[120:121], v[118:119]
	v_cvt_pk_bf16_f32 v25, v2, v3
	v_pk_mul_f32 v[50:51], v[92:93], v[50:51]
	v_add_f32_e32 v40, 1.0, v40
	v_rcp_f32_e32 v40, v40
	v_pk_fma_f32 v[2:3], v[116:117], v[2:3], v[50:51]
	v_lshlrev_b32_e32 v50, 16, v37
	v_and_b32_e32 v51, 0xffff0000, v37
	v_mul_f32_e32 v40, v133, v40
	v_mul_f32_e32 v45, 0x3fb8aa3b, v40
	v_add_f32_e32 v40, v40, v40
	v_mul_f32_e32 v40, 0x3fb8aa3b, v40
	v_exp_f32_e32 v40, v40
	v_exp_f32_e32 v45, v45
	v_pk_mul_f32 v[92:93], v[152:153], v[150:151]
	v_cvt_pk_bf16_f32 v33, v2, v3
	v_sub_f32_e32 v40, 1.0, v40
	v_max_f32_e32 v40, 0, v40
	v_sqrt_f32_e32 v47, v40
	v_add_f32_e32 v40, v23, v189
	v_mul_f32_e32 v40, 0xbfb8aa3b, v40
	v_exp_f32_e32 v40, v40
	v_pk_mul_f32 v[50:51], v[92:93], v[50:51]
	v_sub_f32_e32 v55, 1.0, v55
	v_pk_fma_f32 v[2:3], v[148:149], v[2:3], v[50:51]
	v_add_f32_e32 v40, 1.0, v40
	v_rcp_f32_e32 v49, v40
	v_lshlrev_b32_e32 v40, 16, v41
	v_and_b32_e32 v41, 0xffff0000, v41
; __device__ __forceinline__ float* outg(const Ctx& c) { return (float*)(GAS float*)(unsigned long long)c.out; }
; __device__ __forceinline__ u32x4 pack8(const float (&f)[8]) { u32x4 w; w.x = pk2(f[0], f[1]); w.y = pk2(f[2], f[3]); w.z = pk2(f[4], f[5]); w.w = pk2(f[6], f[7]); return w; }
; template <int FINAL>
; __device__ __forceinline__ void phase_lru(const Ctx& c, int p, int l) {
;     ...
;             if (FINAL) *(u32x4*)(Z + row * ZW + C_LRU + ch) = pack8(x);
;           }
;         }
;         if (!FINAL) { float* ca = car + (size_t)s * 2048 + ch;
; #pragma unroll
;             for (int j = 0; j < 8; ++j) { ca[j] = A[j]; ca[1024 + j] = B[j]; } }
;         else if (g.c == g.nch - 1) { float* o = outg(c) + (sq.sample ? O_SLRU + ((size_t)l * DB + sq.b) * D : O_PLRU + ((size_t)l * NB + sq.b) * D) + ch;
; #pragma unroll
;             for (int j = 0; j < 8; ++j) o[j] = B[j]; }
	v_cvt_pk_bf16_f32 v37, v2, v3
	v_pk_mul_f32 v[46:47], v[48:49], v[46:47]
	v_lshlrev_b32_e32 v48, 16, v26
	v_pk_mul_f32 v[40:41], v[46:47], v[40:41]
	v_add_f32_e32 v47, v17, v191
	v_pk_fma_f32 v[2:3], v[44:45], v[2:3], v[40:41]
	v_add_f32_e32 v40, v8, v184
	v_mul_f32_e32 v40, 0xbfb8aa3b, v40
	v_exp_f32_e32 v40, v40
	v_mul_f32_e32 v47, 0xbfb8aa3b, v47
	v_exp_f32_e32 v47, v47
	v_and_b32_e32 v49, 0xffff0000, v26
	v_add_f32_e32 v40, 1.0, v40
	v_rcp_f32_e32 v40, v40
	v_pk_mul_f32 v[50:51], v[90:91], v[88:89]
	v_add_f32_e32 v47, 1.0, v47
	v_pk_mul_f32 v[48:49], v[50:51], v[48:49]
	v_mul_f32_e32 v41, v134, v40
	v_mul_f32_e32 v40, 0x3fb8aa3b, v41
	v_add_f32_e32 v41, v41, v41
	v_mul_f32_e32 v41, 0x3fb8aa3b, v41
	v_exp_f32_e32 v41, v41
	v_rcp_f32_e32 v47, v47
	v_pk_fma_f32 v[4:5], v[4:5], v[86:87], v[48:49]
	v_lshlrev_b32_e32 v48, 16, v34
	v_sub_f32_e32 v41, 1.0, v41
	v_max_f32_e32 v41, 0, v41
	v_sqrt_f32_e32 v44, v41
	v_add_f32_e32 v41, v16, v190
	v_mul_f32_e32 v41, 0xbfb8aa3b, v41
	v_exp_f32_e32 v41, v41
	v_and_b32_e32 v49, 0xffff0000, v34
	v_pk_mul_f32 v[50:51], v[114:115], v[112:113]
	v_exp_f32_e32 v40, v40
	v_add_f32_e32 v41, 1.0, v41
	v_rcp_f32_e32 v46, v41
	v_add_f32_e32 v41, v9, v185
	v_mul_f32_e32 v41, 0xbfb8aa3b, v41
	v_exp_f32_e32 v41, v41
	v_pk_mul_f32 v[48:49], v[50:51], v[48:49]
	v_cvt_pk_bf16_f32 v26, v4, v5
	v_pk_fma_f32 v[4:5], v[110:111], v[4:5], v[48:49]
	v_add_f32_e32 v41, 1.0, v41
	v_rcp_f32_e32 v41, v41
	v_lshlrev_b32_e32 v48, 16, v38
	v_and_b32_e32 v49, 0xffff0000, v38
	v_pk_mul_f32 v[50:51], v[156:157], v[154:155]
	v_mul_f32_e32 v45, v135, v41
	v_mul_f32_e32 v41, 0x3fb8aa3b, v45
	v_add_f32_e32 v45, v45, v45
	v_mul_f32_e32 v45, 0x3fb8aa3b, v45
	v_exp_f32_e32 v45, v45
	v_exp_f32_e32 v41, v41
	v_pk_mul_f32 v[48:49], v[50:51], v[48:49]
	v_cvt_pk_bf16_f32 v34, v4, v5
	v_sub_f32_e32 v45, 1.0, v45
	v_max_f32_e32 v45, 0, v45
	v_sqrt_f32_e32 v45, v45
	v_pk_fma_f32 v[4:5], v[58:59], v[4:5], v[48:49]
	v_lshlrev_b32_e32 v48, 16, v42
	v_and_b32_e32 v49, 0xffff0000, v42
	v_pk_mul_f32 v[44:45], v[46:47], v[44:45]
	v_cvt_pk_bf16_f32 v38, v4, v5
	v_pk_mul_f32 v[44:45], v[44:45], v[48:49]
	v_max_f32_e32 v55, 0, v55
	v_pk_fma_f32 v[4:5], v[40:41], v[4:5], v[44:45]
	v_add_f32_e32 v40, v10, v186
	v_mul_f32_e32 v40, 0xbfb8aa3b, v40
	v_exp_f32_e32 v40, v40
	v_sqrt_f32_e32 v55, v55
	v_lshlrev_b32_e32 v48, 16, v27
	v_and_b32_e32 v49, 0xffff0000, v27
	v_add_f32_e32 v40, 1.0, v40
	v_rcp_f32_e32 v40, v40
	v_pk_mul_f32 v[50:51], v[84:85], v[82:83]
	v_mul_f32_e32 v41, v144, v40
	v_mul_f32_e32 v40, 0x3fb8aa3b, v41
	v_add_f32_e32 v41, v41, v41
	v_mul_f32_e32 v41, 0x3fb8aa3b, v41
	v_exp_f32_e32 v41, v41
	v_pk_mul_f32 v[48:49], v[50:51], v[48:49]
	v_pk_mul_f32 v[50:51], v[108:109], v[106:107]
	v_pk_fma_f32 v[6:7], v[6:7], v[80:81], v[48:49]
	v_sub_f32_e32 v41, 1.0, v41
	v_max_f32_e32 v41, 0, v41
	v_sqrt_f32_e32 v44, v41
	v_add_f32_e32 v41, v18, v192
	v_mul_f32_e32 v41, 0xbfb8aa3b, v41
	v_exp_f32_e32 v41, v41
	v_lshlrev_b32_e32 v48, 16, v35
	v_and_b32_e32 v49, 0xffff0000, v35
	v_pk_mul_f32 v[48:49], v[50:51], v[48:49]
	v_add_f32_e32 v41, 1.0, v41
	v_rcp_f32_e32 v46, v41
	v_add_f32_e32 v41, v11, v187
	v_mul_f32_e32 v41, 0xbfb8aa3b, v41
	v_exp_f32_e32 v41, v41
	v_cvt_pk_bf16_f32 v27, v6, v7
	v_pk_fma_f32 v[6:7], v[104:105], v[6:7], v[48:49]
	v_lshlrev_b32_e32 v48, 16, v39
	v_add_f32_e32 v41, 1.0, v41
	v_rcp_f32_e32 v41, v41
	v_and_b32_e32 v49, 0xffff0000, v39
	v_pk_mul_f32 v[50:51], v[56:57], v[54:55]
	v_exp_f32_e32 v40, v40
	v_mul_f32_e32 v42, v145, v41
	v_mul_f32_e32 v41, 0x3fb8aa3b, v42
	v_add_f32_e32 v42, v42, v42
	v_mul_f32_e32 v42, 0x3fb8aa3b, v42
	v_exp_f32_e32 v42, v42
	v_exp_f32_e32 v41, v41
	v_pk_mul_f32 v[48:49], v[50:51], v[48:49]
	v_cvt_pk_bf16_f32 v35, v6, v7
	v_sub_f32_e32 v42, 1.0, v42
	v_max_f32_e32 v42, 0, v42
	v_sqrt_f32_e32 v45, v42
	v_add_f32_e32 v42, v19, v193
	v_mul_f32_e32 v42, 0xbfb8aa3b, v42
	v_exp_f32_e32 v42, v42
	v_pk_fma_f32 v[6:7], v[52:53], v[6:7], v[48:49]
	v_add_f32_e32 v42, 1.0, v42
	v_rcp_f32_e32 v47, v42
	v_cvt_pk_bf16_f32 v39, v6, v7
	v_lshlrev_b32_e32 v42, 16, v43
	v_and_b32_e32 v43, 0xffff0000, v43
	global_store_dwordx4 v[72:73], v[24:27], off
	global_store_dwordx4 v[74:75], v[32:35], off offset:512
	global_store_dwordx4 v[76:77], v[36:39], off offset:1024
	v_pk_mul_f32 v[24:25], v[46:47], v[44:45]
	v_cvt_pk_bf16_f32 v26, v4, v5
	v_pk_mul_f32 v[24:25], v[24:25], v[42:43]
	s_nop 0
	v_pk_fma_f32 v[6:7], v[40:41], v[6:7], v[24:25]
	v_cvt_pk_bf16_f32 v24, v0, v1
	v_cvt_pk_bf16_f32 v25, v2, v3
	v_cvt_pk_bf16_f32 v27, v6, v7
	global_store_dwordx4 v[78:79], v[24:27], off offset:1536
	s_andn2_b64 exec, exec, s[4:5]
	s_cbranch_execnz .LBB0_1143
	s_waitcnt vmcnt(0)
	s_or_b64 exec, exec, s[4:5]
	s_and_saveexec_b64 s[4:5], s[10:11]
	s_cbranch_execz .LBB0_1131
	v_readlane_b32 s10, v254, 25
	v_readlane_b32 s0, v254, 27
	v_readlane_b32 s11, v254, 26
	v_mov_b32_e32 v8, s10
	v_mov_b32_e32 v9, s0
	v_cndmask_b32_e64 v30, v8, v9, s[2:3]
	v_cndmask_b32_e64 v8, v179, v180, s[2:3]
	v_lshl_add_u64 v[10:11], v[30:31], 0, v[66:67]
	v_readlane_b32 s2, v254, 43
	v_lshlrev_b64 v[10:11], 12, v[10:11]
	v_readlane_b32 s3, v254, 44
	v_mov_b32_e32 v9, v31
	v_lshlrev_b32_e32 v30, 2, v64
	v_lshl_add_u64 v[10:11], s[2:3], 0, v[10:11]
	v_lshl_add_u64 v[8:9], v[10:11], 0, v[8:9]
	v_lshl_add_u64 v[8:9], v[8:9], 0, v[30:31]
	global_store_dwordx4 v[8:9], v[0:3], off
	global_store_dwordx4 v[8:9], v[4:7], off offset:16
	s_branch .LBB0_1131
